# v20 plus: write-through (sc1) stores for the phase outputs of P0 (XN, transposed weights) and P3 (H) so the barrier release flush has little to write back
# baseline (speedup 1.0000x reference)
; #define LAS __attribute__((address_space(3)))
; __device__ __forceinline__ unsigned cvt_pk_bf16(float lo, float hi) { f32x2_t v = {lo, hi}; bf16x2_t b = __builtin_convertvector(v, bf16x2_t); return __builtin_bit_cast(unsigned, b); }
; __host__ __device__ __forceinline__ int prow(int n) { const int cc = n & 255; return (n & ~255) | (((cc >> 5) & 1) * 128 + (cc >> 6) * 32 + ((cc >> 2) & 1) * 16 + ((cc >> 3) & 3) * 4 + (cc & 3)); }
; __device__ __forceinline__ void p0_transpose_item(const float* W, int K, int N, bf16_t* WT, int ldo, int koff, LAS float* scr, int item, int lane) {
;     const int nblk = N / 32, kb = item / nblk, nb = item % nblk, k0 = 64 * kb, n0 = 32 * nb;
;     f32x4 t[8];
; #pragma unroll
;     for (int i = 0; i < 8; ++i) { const int id = lane + 64 * i; t[i] = __builtin_nontemporal_load((const f32x4*)(W + (size_t)(k0 + (id >> 3)) * N + n0 + 4 * (id & 7))); }
; #pragma unroll
;     for (int i = 0; i < 8; ++i) { const int id = lane + 64 * i; LAS float* d = scr + (id >> 3) * 33 + 4 * (id & 7); d[0] = t[i].x; d[1] = t[i].y; d[2] = t[i].z; d[3] = t[i].w; }
;     asm volatile("s_waitcnt lgkmcnt(0)" ::: "memory");
;     const int c = lane & 7;
; #pragma unroll
;     for (int j = 0; j < 4; ++j) { const int n = (lane >> 3) + 8 * j; const LAS float* s = scr + (8 * c) * 33 + n;
;         u32x4 o; o.x = cvt_pk_bf16(s[0 * 33], s[1 * 33]); o.y = cvt_pk_bf16(s[2 * 33], s[3 * 33]); o.z = cvt_pk_bf16(s[4 * 33], s[5 * 33]); o.w = cvt_pk_bf16(s[6 * 33], s[7 * 33]);
;         *(u32x4*)(WT + (size_t)prow(n0 + n) * ldo + koff + k0 + 8 * c) = o; }
;     asm volatile("s_waitcnt lgkmcnt(0)" ::: "memory");
; }
; template <bool COOP>
; __global__ void __launch_bounds__(512, 2) mega(Args a) {
;     ...
;             if (r < I_IN) { p0_transpose_item(w_in, DM, NIN, WinT, DM, 0, scr, r, lane); continue; } r -= I_IN;
;             if (r < I_PS) { p0_transpose_item(wpsb, 512, DM, WpT, DM, 0, scr, r, lane); continue; } r -= I_PS;
;             if (r < I_PS) { p0_transpose_item(wpcb, 512, DM, WpT, DM, 512, scr, r, lane); continue; } r -= I_PS;
;             p0_transpose_item(wout, DM, DM, WoutT, DM, 0, scr, r, lane);
.LBB0_23:
	s_cmpk_gt_i32 s19, 0xbff
	s_mov_b64 s[6:7], -1
	s_cbranch_scc0 .LBB0_33
	s_cmpk_gt_u32 s19, 0xcff
	s_cbranch_scc0 .LBB0_30
	s_cmpk_gt_u32 s19, 0xdff
	s_cbranch_scc0 .LBB0_27
	s_add_i32 s6, s16, 0x1e400
	s_and_b32 s7, s6, 0x1ffc0
	s_and_b32 s6, s5, 0x3e0
	s_lshl_b32 s10, s6, 2
	v_or_b32_e32 v0, s7, v18
	v_lshl_add_u64 v[72:73], v[2:3], 0, s[10:11]
	v_lshlrev_b32_e32 v0, 12, v0
	v_lshl_add_u64 v[44:45], v[72:73], 0, v[0:1]
	v_or_b32_e32 v0, s7, v19
	v_lshlrev_b32_e32 v0, 12, v0
	v_lshl_add_u64 v[48:49], v[72:73], 0, v[0:1]
	v_or_b32_e32 v0, s7, v20
	v_lshlrev_b32_e32 v0, 12, v0
	v_lshl_add_u64 v[52:53], v[72:73], 0, v[0:1]
	v_or_b32_e32 v0, s7, v21
	v_lshlrev_b32_e32 v0, 12, v0
	v_lshl_add_u64 v[56:57], v[72:73], 0, v[0:1]
	v_or_b32_e32 v0, s7, v22
	v_lshlrev_b32_e32 v0, 12, v0
	v_lshl_add_u64 v[60:61], v[72:73], 0, v[0:1]
	v_or_b32_e32 v0, s7, v23
	v_lshlrev_b32_e32 v0, 12, v0
	v_lshl_add_u64 v[64:65], v[72:73], 0, v[0:1]
	global_load_dwordx4 v[44:47], v[44:45], off nt
	s_nop 0
	global_load_dwordx4 v[48:51], v[48:49], off nt
	s_nop 0
	global_load_dwordx4 v[52:55], v[52:53], off nt
	s_nop 0
	global_load_dwordx4 v[56:59], v[56:57], off nt
	s_nop 0
	global_load_dwordx4 v[60:63], v[60:61], off nt
	s_nop 0
	global_load_dwordx4 v[64:67], v[64:65], off nt
	v_or_b32_e32 v0, s7, v24
	v_lshlrev_b32_e32 v0, 12, v0
	v_lshl_add_u64 v[68:69], v[72:73], 0, v[0:1]
	v_or_b32_e32 v0, s7, v25
	global_load_dwordx4 v[68:71], v[68:69], off nt
	v_lshlrev_b32_e32 v0, 12, v0
	v_lshl_add_u64 v[72:73], v[72:73], 0, v[0:1]
	global_load_dwordx4 v[72:75], v[72:73], off nt
	v_or_b32_e32 v0, s6, v18
	v_or_b32_e32 v76, s6, v19
	v_lshlrev_b32_e32 v0, 2, v0
	s_and_b32 s20, s14, 0x60
	v_bitop3_b32 v78, s6, v43, v18 bitop3:0xc8
	v_lshlrev_b32_e32 v80, 2, v76
	v_lshrrev_b32_e32 v81, 1, v76
	v_and_b32_e32 v0, 0x90, v0
	v_bitop3_b32 v79, s6, v43, v19 bitop3:0xc8
	s_lshl_b32 s10, s7, 1
	v_and_b32_e32 v80, 0x90, v80
	v_and_b32_e32 v81, 0x64, v81
	v_or3_b32 v0, s20, v78, v0
	v_lshl_add_u64 v[76:77], v[4:5], 0, s[10:11]
	v_or3_b32 v80, v79, v81, v80
	v_lshlrev_b32_e32 v0, 11, v0
	v_lshl_add_u64 v[78:79], v[76:77], 0, v[0:1]
	v_lshlrev_b32_e32 v0, 11, v80
	v_lshl_add_u64 v[80:81], v[76:77], 0, v[0:1]
	v_or_b32_e32 v0, s6, v20
	s_waitcnt vmcnt(7)
	ds_write2_b32 v28, v44, v45 offset1:1
	ds_write2_b32 v28, v46, v47 offset0:2 offset1:3
	s_waitcnt vmcnt(6)
	ds_write2_b32 v29, v48, v49 offset1:1
	ds_write2_b32 v30, v50, v51 offset1:1
	s_waitcnt vmcnt(5)
	ds_write2_b32 v31, v52, v53 offset1:1
	ds_write2_b32 v32, v54, v55 offset1:1
	s_waitcnt vmcnt(4)
	ds_write2_b32 v33, v56, v57 offset1:1
	ds_write2_b32 v34, v58, v59 offset1:1
	s_waitcnt vmcnt(3)
	ds_write2_b32 v35, v60, v61 offset1:1
	ds_write2_b32 v36, v62, v63 offset1:1
	s_waitcnt vmcnt(2)
	ds_write2_b32 v37, v64, v65 offset1:1
	ds_write2_b32 v38, v66, v67 offset1:1
	s_waitcnt vmcnt(1)
	ds_write2_b32 v39, v68, v69 offset1:1
	ds_write2_b32 v40, v70, v71 offset1:1
	s_waitcnt vmcnt(0)
	ds_write2_b32 v41, v72, v73 offset1:1
	ds_write2_b32 v42, v74, v75 offset1:1
	s_waitcnt lgkmcnt(0)
	ds_read2_b32 v[48:49], v26 offset0:33 offset1:41
	ds_read2_b32 v[50:51], v26 offset1:8
	ds_read2_b32 v[52:53], v26 offset0:66 offset1:74
	ds_read2_b32 v[54:55], v26 offset0:99 offset1:107
	ds_read2_b32 v[56:57], v26 offset0:132 offset1:140
	ds_read2_b32 v[58:59], v26 offset0:165 offset1:173
	ds_read2_b32 v[60:61], v26 offset0:198 offset1:206
	ds_read2_b32 v[62:63], v26 offset0:231 offset1:239
	ds_read2_b32 v[64:65], v26 offset0:49 offset1:57
	ds_read2_b32 v[66:67], v26 offset0:16 offset1:24
	ds_read2_b32 v[68:69], v26 offset0:82 offset1:90
	ds_read2_b32 v[70:71], v26 offset0:115 offset1:123
	ds_read2_b32 v[72:73], v26 offset0:148 offset1:156
	ds_read2_b32 v[74:75], v26 offset0:181 offset1:189
	ds_read2_b32 v[82:83], v26 offset0:214 offset1:222
	ds_read2_b32 v[84:85], v26 offset0:247 offset1:255
	s_waitcnt lgkmcnt(14)
	v_cvt_pk_bf16_f32 v44, v50, v48
	s_waitcnt lgkmcnt(12)
	v_cvt_pk_bf16_f32 v45, v52, v54
	s_waitcnt lgkmcnt(10)
	v_cvt_pk_bf16_f32 v46, v56, v58
	s_waitcnt lgkmcnt(8)
	v_cvt_pk_bf16_f32 v47, v60, v62
	v_cvt_pk_bf16_f32 v48, v51, v49
	v_cvt_pk_bf16_f32 v49, v53, v55
	v_cvt_pk_bf16_f32 v50, v57, v59
	v_cvt_pk_bf16_f32 v51, v61, v63
	global_store_dwordx4 v[78:79], v[44:47], off sc1
	global_store_dwordx4 v[80:81], v[48:51], off sc1
	s_waitcnt lgkmcnt(6)
	v_cvt_pk_bf16_f32 v52, v66, v64
	v_lshlrev_b32_e32 v44, 2, v0
	v_lshrrev_b32_e32 v0, 1, v0
	v_and_b32_e32 v44, 0x90, v44
	v_and_b32_e32 v0, 0x68, v0
	v_bitop3_b32 v45, s6, v43, v20 bitop3:0xc8
	v_or3_b32 v0, v45, v0, v44
	v_lshlrev_b32_e32 v0, 11, v0
	v_lshl_add_u64 v[44:45], v[76:77], 0, v[0:1]
	v_or_b32_e32 v0, s6, v21
	v_lshlrev_b32_e32 v48, 2, v0
	v_lshrrev_b32_e32 v0, 1, v0
	v_and_b32_e32 v48, 0x90, v48
	v_and_b32_e32 v0, 0x6c, v0
	v_bitop3_b32 v49, s6, v43, v21 bitop3:0xc8
	v_or3_b32 v0, v49, v0, v48
	s_waitcnt lgkmcnt(4)
	v_cvt_pk_bf16_f32 v53, v68, v70
	s_waitcnt lgkmcnt(2)
	v_cvt_pk_bf16_f32 v54, v72, v74
	s_waitcnt lgkmcnt(0)
	v_cvt_pk_bf16_f32 v55, v82, v84
	v_lshlrev_b32_e32 v0, 11, v0
	global_store_dwordx4 v[44:45], v[52:55], off sc1
	v_cvt_pk_bf16_f32 v44, v67, v65
	v_cvt_pk_bf16_f32 v45, v69, v71
	v_cvt_pk_bf16_f32 v46, v73, v75
	v_cvt_pk_bf16_f32 v47, v83, v85
	v_lshl_add_u64 v[48:49], v[76:77], 0, v[0:1]
	global_store_dwordx4 v[48:49], v[44:47], off sc1
	s_waitcnt lgkmcnt(0)
	s_mov_b64 s[6:7], 0
; #define LAS __attribute__((address_space(3)))
; __device__ __forceinline__ unsigned cvt_pk_bf16(float lo, float hi) { f32x2_t v = {lo, hi}; bf16x2_t b = __builtin_convertvector(v, bf16x2_t); return __builtin_bit_cast(unsigned, b); }
; __host__ __device__ __forceinline__ int prow(int n) { const int cc = n & 255; return (n & ~255) | (((cc >> 5) & 1) * 128 + (cc >> 6) * 32 + ((cc >> 2) & 1) * 16 + ((cc >> 3) & 3) * 4 + (cc & 3)); }
; __device__ __forceinline__ void p0_transpose_item(const float* W, int K, int N, bf16_t* WT, int ldo, int koff, LAS float* scr, int item, int lane) {
;     const int nblk = N / 32, kb = item / nblk, nb = item % nblk, k0 = 64 * kb, n0 = 32 * nb;
;     f32x4 t[8];
; #pragma unroll
;     for (int i = 0; i < 8; ++i) { const int id = lane + 64 * i; t[i] = __builtin_nontemporal_load((const f32x4*)(W + (size_t)(k0 + (id >> 3)) * N + n0 + 4 * (id & 7))); }
; #pragma unroll
;     for (int i = 0; i < 8; ++i) { const int id = lane + 64 * i; LAS float* d = scr + (id >> 3) * 33 + 4 * (id & 7); d[0] = t[i].x; d[1] = t[i].y; d[2] = t[i].z; d[3] = t[i].w; }
;     asm volatile("s_waitcnt lgkmcnt(0)" ::: "memory");
;     const int c = lane & 7;
; #pragma unroll
;     for (int j = 0; j < 4; ++j) { const int n = (lane >> 3) + 8 * j; const LAS float* s = scr + (8 * c) * 33 + n;
;         u32x4 o; o.x = cvt_pk_bf16(s[0 * 33], s[1 * 33]); o.y = cvt_pk_bf16(s[2 * 33], s[3 * 33]); o.z = cvt_pk_bf16(s[4 * 33], s[5 * 33]); o.w = cvt_pk_bf16(s[6 * 33], s[7 * 33]);
;         *(u32x4*)(WT + (size_t)prow(n0 + n) * ldo + koff + k0 + 8 * c) = o; }
;     asm volatile("s_waitcnt lgkmcnt(0)" ::: "memory");
; }
; template <bool COOP>
; __global__ void __launch_bounds__(512, 2) mega(Args a) {
;     ...
;             if (r < I_IN) { p0_transpose_item(w_in, DM, NIN, WinT, DM, 0, scr, r, lane); continue; } r -= I_IN;
;             if (r < I_PS) { p0_transpose_item(wpsb, 512, DM, WpT, DM, 0, scr, r, lane); continue; } r -= I_PS;
;             if (r < I_PS) { p0_transpose_item(wpcb, 512, DM, WpT, DM, 512, scr, r, lane); continue; } r -= I_PS;
;             p0_transpose_item(wout, DM, DM, WoutT, DM, 0, scr, r, lane);
.LBB0_27:
	s_andn2_b64 vcc, exec, s[6:7]
	s_cbranch_vccnz .LBB0_29
	s_and_b32 s7, s16, 0x1c0
	s_and_b32 s6, s5, 0x3e0
	s_lshl_b32 s10, s6, 2
	v_or_b32_e32 v0, s7, v18
	v_lshl_add_u64 v[72:73], v[6:7], 0, s[10:11]
	v_lshlrev_b32_e32 v0, 12, v0
	v_lshl_add_u64 v[44:45], v[72:73], 0, v[0:1]
	v_or_b32_e32 v0, s7, v19
	v_lshlrev_b32_e32 v0, 12, v0
	v_lshl_add_u64 v[48:49], v[72:73], 0, v[0:1]
	v_or_b32_e32 v0, s7, v20
	v_lshlrev_b32_e32 v0, 12, v0
	v_lshl_add_u64 v[52:53], v[72:73], 0, v[0:1]
	v_or_b32_e32 v0, s7, v21
	v_lshlrev_b32_e32 v0, 12, v0
	v_lshl_add_u64 v[56:57], v[72:73], 0, v[0:1]
	v_or_b32_e32 v0, s7, v22
	v_lshlrev_b32_e32 v0, 12, v0
	v_lshl_add_u64 v[60:61], v[72:73], 0, v[0:1]
	v_or_b32_e32 v0, s7, v23
	v_lshlrev_b32_e32 v0, 12, v0
	v_lshl_add_u64 v[64:65], v[72:73], 0, v[0:1]
	global_load_dwordx4 v[44:47], v[44:45], off nt
	s_nop 0
	global_load_dwordx4 v[48:51], v[48:49], off nt
	s_nop 0
	global_load_dwordx4 v[52:55], v[52:53], off nt
	s_nop 0
	global_load_dwordx4 v[56:59], v[56:57], off nt
	s_nop 0
	global_load_dwordx4 v[60:63], v[60:61], off nt
	s_nop 0
	global_load_dwordx4 v[64:67], v[64:65], off nt
	v_or_b32_e32 v0, s7, v24
	v_lshlrev_b32_e32 v0, 12, v0
	v_lshl_add_u64 v[68:69], v[72:73], 0, v[0:1]
	v_or_b32_e32 v0, s7, v25
	global_load_dwordx4 v[68:71], v[68:69], off nt
	v_lshlrev_b32_e32 v0, 12, v0
	v_lshl_add_u64 v[72:73], v[72:73], 0, v[0:1]
	global_load_dwordx4 v[72:75], v[72:73], off nt
	v_or_b32_e32 v0, s6, v18
	v_or_b32_e32 v76, s6, v19
	v_lshlrev_b32_e32 v0, 2, v0
	s_and_b32 s20, s14, 0x60
	v_bitop3_b32 v78, s6, v43, v18 bitop3:0xc8
	v_lshlrev_b32_e32 v80, 2, v76
	v_lshrrev_b32_e32 v81, 1, v76
	v_and_b32_e32 v0, 0x90, v0
	v_bitop3_b32 v79, s6, v43, v19 bitop3:0xc8
	s_lshl_b32 s10, s7, 1
	v_and_b32_e32 v80, 0x90, v80
	v_and_b32_e32 v81, 0x64, v81
	v_or3_b32 v0, s20, v78, v0
	v_lshl_add_u64 v[76:77], v[8:9], 0, s[10:11]
	v_or3_b32 v80, v79, v81, v80
	v_lshlrev_b32_e32 v0, 11, v0
	v_lshl_add_u64 v[78:79], v[76:77], 0, v[0:1]
	v_lshlrev_b32_e32 v0, 11, v80
	v_lshl_add_u64 v[80:81], v[76:77], 0, v[0:1]
	v_or_b32_e32 v0, s6, v20
	s_waitcnt vmcnt(7)
	ds_write2_b32 v28, v44, v45 offset1:1
	ds_write2_b32 v28, v46, v47 offset0:2 offset1:3
	s_waitcnt vmcnt(6)
	ds_write2_b32 v29, v48, v49 offset1:1
	ds_write2_b32 v30, v50, v51 offset1:1
	s_waitcnt vmcnt(5)
	ds_write2_b32 v31, v52, v53 offset1:1
	ds_write2_b32 v32, v54, v55 offset1:1
	s_waitcnt vmcnt(4)
	ds_write2_b32 v33, v56, v57 offset1:1
	ds_write2_b32 v34, v58, v59 offset1:1
	s_waitcnt vmcnt(3)
	ds_write2_b32 v35, v60, v61 offset1:1
	ds_write2_b32 v36, v62, v63 offset1:1
	s_waitcnt vmcnt(2)
	ds_write2_b32 v37, v64, v65 offset1:1
	ds_write2_b32 v38, v66, v67 offset1:1
	s_waitcnt vmcnt(1)
	ds_write2_b32 v39, v68, v69 offset1:1
	ds_write2_b32 v40, v70, v71 offset1:1
	s_waitcnt vmcnt(0)
	ds_write2_b32 v41, v72, v73 offset1:1
	ds_write2_b32 v42, v74, v75 offset1:1
	s_waitcnt lgkmcnt(0)
	ds_read2_b32 v[48:49], v26 offset0:33 offset1:41
	ds_read2_b32 v[50:51], v26 offset1:8
	ds_read2_b32 v[52:53], v26 offset0:66 offset1:74
	ds_read2_b32 v[54:55], v26 offset0:99 offset1:107
	ds_read2_b32 v[56:57], v26 offset0:132 offset1:140
	ds_read2_b32 v[58:59], v26 offset0:165 offset1:173
	ds_read2_b32 v[60:61], v26 offset0:198 offset1:206
	ds_read2_b32 v[62:63], v26 offset0:231 offset1:239
	ds_read2_b32 v[64:65], v26 offset0:49 offset1:57
	ds_read2_b32 v[66:67], v26 offset0:16 offset1:24
	ds_read2_b32 v[68:69], v26 offset0:82 offset1:90
	ds_read2_b32 v[70:71], v26 offset0:115 offset1:123
	ds_read2_b32 v[72:73], v26 offset0:148 offset1:156
	ds_read2_b32 v[74:75], v26 offset0:181 offset1:189
	ds_read2_b32 v[82:83], v26 offset0:214 offset1:222
	ds_read2_b32 v[84:85], v26 offset0:247 offset1:255
	s_waitcnt lgkmcnt(14)
	v_cvt_pk_bf16_f32 v44, v50, v48
	s_waitcnt lgkmcnt(12)
	v_cvt_pk_bf16_f32 v45, v52, v54
	s_waitcnt lgkmcnt(10)
	v_cvt_pk_bf16_f32 v46, v56, v58
	s_waitcnt lgkmcnt(8)
	v_cvt_pk_bf16_f32 v47, v60, v62
	v_cvt_pk_bf16_f32 v48, v51, v49
	v_cvt_pk_bf16_f32 v49, v53, v55
	v_cvt_pk_bf16_f32 v50, v57, v59
	v_cvt_pk_bf16_f32 v51, v61, v63
	global_store_dwordx4 v[78:79], v[44:47], off sc1
	global_store_dwordx4 v[80:81], v[48:51], off sc1
	s_waitcnt lgkmcnt(6)
	v_cvt_pk_bf16_f32 v52, v66, v64
	v_lshlrev_b32_e32 v44, 2, v0
	v_lshrrev_b32_e32 v0, 1, v0
	v_and_b32_e32 v44, 0x90, v44
	v_and_b32_e32 v0, 0x68, v0
	v_bitop3_b32 v45, s6, v43, v20 bitop3:0xc8
	v_or3_b32 v0, v45, v0, v44
	v_lshlrev_b32_e32 v0, 11, v0
	v_lshl_add_u64 v[44:45], v[76:77], 0, v[0:1]
	v_or_b32_e32 v0, s6, v21
	v_lshlrev_b32_e32 v48, 2, v0
	v_lshrrev_b32_e32 v0, 1, v0
	v_and_b32_e32 v48, 0x90, v48
	v_and_b32_e32 v0, 0x6c, v0
	v_bitop3_b32 v49, s6, v43, v21 bitop3:0xc8
	v_or3_b32 v0, v49, v0, v48
	s_waitcnt lgkmcnt(4)
	v_cvt_pk_bf16_f32 v53, v68, v70
	s_waitcnt lgkmcnt(2)
	v_cvt_pk_bf16_f32 v54, v72, v74
	s_waitcnt lgkmcnt(0)
	v_cvt_pk_bf16_f32 v55, v82, v84
	v_lshlrev_b32_e32 v0, 11, v0
	global_store_dwordx4 v[44:45], v[52:55], off sc1
	v_cvt_pk_bf16_f32 v44, v67, v65
	v_cvt_pk_bf16_f32 v45, v69, v71
	v_cvt_pk_bf16_f32 v46, v73, v75
	v_cvt_pk_bf16_f32 v47, v83, v85
	v_lshl_add_u64 v[48:49], v[76:77], 0, v[0:1]
	global_store_dwordx4 v[48:49], v[44:47], off sc1
	s_waitcnt lgkmcnt(0)

; #define LAS __attribute__((address_space(3)))
; __device__ __forceinline__ unsigned cvt_pk_bf16(float lo, float hi) { f32x2_t v = {lo, hi}; bf16x2_t b = __builtin_convertvector(v, bf16x2_t); return __builtin_bit_cast(unsigned, b); }
; __host__ __device__ __forceinline__ int prow(int n) { const int cc = n & 255; return (n & ~255) | (((cc >> 5) & 1) * 128 + (cc >> 6) * 32 + ((cc >> 2) & 1) * 16 + ((cc >> 3) & 3) * 4 + (cc & 3)); }
; __device__ __forceinline__ void p0_transpose_item(const float* W, int K, int N, bf16_t* WT, int ldo, int koff, LAS float* scr, int item, int lane) {
;     const int nblk = N / 32, kb = item / nblk, nb = item % nblk, k0 = 64 * kb, n0 = 32 * nb;
;     f32x4 t[8];
; #pragma unroll
;     for (int i = 0; i < 8; ++i) { const int id = lane + 64 * i; t[i] = __builtin_nontemporal_load((const f32x4*)(W + (size_t)(k0 + (id >> 3)) * N + n0 + 4 * (id & 7))); }
; #pragma unroll
;     for (int i = 0; i < 8; ++i) { const int id = lane + 64 * i; LAS float* d = scr + (id >> 3) * 33 + 4 * (id & 7); d[0] = t[i].x; d[1] = t[i].y; d[2] = t[i].z; d[3] = t[i].w; }
;     asm volatile("s_waitcnt lgkmcnt(0)" ::: "memory");
;     const int c = lane & 7;
; #pragma unroll
;     for (int j = 0; j < 4; ++j) { const int n = (lane >> 3) + 8 * j; const LAS float* s = scr + (8 * c) * 33 + n;
;         u32x4 o; o.x = cvt_pk_bf16(s[0 * 33], s[1 * 33]); o.y = cvt_pk_bf16(s[2 * 33], s[3 * 33]); o.z = cvt_pk_bf16(s[4 * 33], s[5 * 33]); o.w = cvt_pk_bf16(s[6 * 33], s[7 * 33]);
;         *(u32x4*)(WT + (size_t)prow(n0 + n) * ldo + koff + k0 + 8 * c) = o; }
;     asm volatile("s_waitcnt lgkmcnt(0)" ::: "memory");
; }
; template <bool COOP>
; __global__ void __launch_bounds__(512, 2) mega(Args a) {
;     ...
;             if (r < I_IN) { p0_transpose_item(w_in, DM, NIN, WinT, DM, 0, scr, r, lane); continue; } r -= I_IN;
;             if (r < I_PS) { p0_transpose_item(wpsb, 512, DM, WpT, DM, 0, scr, r, lane); continue; } r -= I_PS;
;             if (r < I_PS) { p0_transpose_item(wpcb, 512, DM, WpT, DM, 512, scr, r, lane); continue; } r -= I_PS;
;             p0_transpose_item(wout, DM, DM, WoutT, DM, 0, scr, r, lane);
.LBB0_30:
	s_andn2_b64 vcc, exec, s[6:7]
	s_cbranch_vccnz .LBB0_32
	s_and_b32 s7, s16, 0x1c0
	s_and_b32 s6, s5, 0x3e0
	s_lshl_b32 s10, s6, 2
	v_or_b32_e32 v0, s7, v18
	v_lshl_add_u64 v[72:73], v[10:11], 0, s[10:11]
	v_lshlrev_b32_e32 v0, 12, v0
	v_lshl_add_u64 v[44:45], v[72:73], 0, v[0:1]
	v_or_b32_e32 v0, s7, v19
	v_lshlrev_b32_e32 v0, 12, v0
	v_lshl_add_u64 v[48:49], v[72:73], 0, v[0:1]
	v_or_b32_e32 v0, s7, v20
	v_lshlrev_b32_e32 v0, 12, v0
	v_lshl_add_u64 v[52:53], v[72:73], 0, v[0:1]
	v_or_b32_e32 v0, s7, v21
	v_lshlrev_b32_e32 v0, 12, v0
	v_lshl_add_u64 v[56:57], v[72:73], 0, v[0:1]
	v_or_b32_e32 v0, s7, v22
	v_lshlrev_b32_e32 v0, 12, v0
	v_lshl_add_u64 v[60:61], v[72:73], 0, v[0:1]
	v_or_b32_e32 v0, s7, v23
	v_lshlrev_b32_e32 v0, 12, v0
	v_lshl_add_u64 v[64:65], v[72:73], 0, v[0:1]
	global_load_dwordx4 v[44:47], v[44:45], off nt
	s_nop 0
	global_load_dwordx4 v[48:51], v[48:49], off nt
	s_nop 0
	global_load_dwordx4 v[52:55], v[52:53], off nt
	s_nop 0
	global_load_dwordx4 v[56:59], v[56:57], off nt
	s_nop 0
	global_load_dwordx4 v[60:63], v[60:61], off nt
	s_nop 0
	global_load_dwordx4 v[64:67], v[64:65], off nt
	v_or_b32_e32 v0, s7, v24
	v_lshlrev_b32_e32 v0, 12, v0
	v_lshl_add_u64 v[68:69], v[72:73], 0, v[0:1]
	v_or_b32_e32 v0, s7, v25
	global_load_dwordx4 v[68:71], v[68:69], off nt
	v_lshlrev_b32_e32 v0, 12, v0
	v_lshl_add_u64 v[72:73], v[72:73], 0, v[0:1]
	global_load_dwordx4 v[72:75], v[72:73], off nt
	v_or_b32_e32 v0, s6, v18
	v_or_b32_e32 v76, s6, v19
	v_lshlrev_b32_e32 v0, 2, v0
	s_and_b32 s20, s14, 0x60
	v_bitop3_b32 v78, s6, v43, v18 bitop3:0xc8
	v_lshlrev_b32_e32 v80, 2, v76
	v_lshrrev_b32_e32 v81, 1, v76
	v_and_b32_e32 v0, 0x90, v0
	v_bitop3_b32 v79, s6, v43, v19 bitop3:0xc8
	s_lshl_b32 s10, s7, 1
	v_and_b32_e32 v80, 0x90, v80
	v_and_b32_e32 v81, 0x64, v81
	v_or3_b32 v0, s20, v78, v0
	v_lshl_add_u64 v[76:77], v[12:13], 0, s[10:11]
	v_or3_b32 v80, v79, v81, v80
	v_lshlrev_b32_e32 v0, 11, v0
	v_lshl_add_u64 v[78:79], v[76:77], 0, v[0:1]
	v_lshlrev_b32_e32 v0, 11, v80
	v_lshl_add_u64 v[80:81], v[76:77], 0, v[0:1]
	v_or_b32_e32 v0, s6, v20
	s_waitcnt vmcnt(7)
	ds_write2_b32 v28, v44, v45 offset1:1
	ds_write2_b32 v28, v46, v47 offset0:2 offset1:3
	s_waitcnt vmcnt(6)
	ds_write2_b32 v29, v48, v49 offset1:1
	ds_write2_b32 v30, v50, v51 offset1:1
	s_waitcnt vmcnt(5)
	ds_write2_b32 v31, v52, v53 offset1:1
	ds_write2_b32 v32, v54, v55 offset1:1
	s_waitcnt vmcnt(4)
	ds_write2_b32 v33, v56, v57 offset1:1
	ds_write2_b32 v34, v58, v59 offset1:1
	s_waitcnt vmcnt(3)
	ds_write2_b32 v35, v60, v61 offset1:1
	ds_write2_b32 v36, v62, v63 offset1:1
	s_waitcnt vmcnt(2)
	ds_write2_b32 v37, v64, v65 offset1:1
	ds_write2_b32 v38, v66, v67 offset1:1
	s_waitcnt vmcnt(1)
	ds_write2_b32 v39, v68, v69 offset1:1
	ds_write2_b32 v40, v70, v71 offset1:1
	s_waitcnt vmcnt(0)
	ds_write2_b32 v41, v72, v73 offset1:1
	ds_write2_b32 v42, v74, v75 offset1:1
	s_waitcnt lgkmcnt(0)
	ds_read2_b32 v[48:49], v26 offset0:33 offset1:41
	ds_read2_b32 v[50:51], v26 offset1:8
	ds_read2_b32 v[52:53], v26 offset0:66 offset1:74
	ds_read2_b32 v[54:55], v26 offset0:99 offset1:107
	ds_read2_b32 v[56:57], v26 offset0:132 offset1:140
	ds_read2_b32 v[58:59], v26 offset0:165 offset1:173
	ds_read2_b32 v[60:61], v26 offset0:198 offset1:206
	ds_read2_b32 v[62:63], v26 offset0:231 offset1:239
	ds_read2_b32 v[64:65], v26 offset0:49 offset1:57
	ds_read2_b32 v[66:67], v26 offset0:16 offset1:24
	ds_read2_b32 v[68:69], v26 offset0:82 offset1:90
	ds_read2_b32 v[70:71], v26 offset0:115 offset1:123
	ds_read2_b32 v[72:73], v26 offset0:148 offset1:156
	ds_read2_b32 v[74:75], v26 offset0:181 offset1:189
	ds_read2_b32 v[82:83], v26 offset0:214 offset1:222
	ds_read2_b32 v[84:85], v26 offset0:247 offset1:255
	s_waitcnt lgkmcnt(14)
	v_cvt_pk_bf16_f32 v44, v50, v48
	s_waitcnt lgkmcnt(12)
	v_cvt_pk_bf16_f32 v45, v52, v54
	s_waitcnt lgkmcnt(10)
	v_cvt_pk_bf16_f32 v46, v56, v58
	s_waitcnt lgkmcnt(8)
	v_cvt_pk_bf16_f32 v47, v60, v62
	v_cvt_pk_bf16_f32 v48, v51, v49
	v_cvt_pk_bf16_f32 v49, v53, v55
	v_cvt_pk_bf16_f32 v50, v57, v59
	v_cvt_pk_bf16_f32 v51, v61, v63
	global_store_dwordx4 v[78:79], v[44:47], off sc1
	global_store_dwordx4 v[80:81], v[48:51], off sc1
	s_waitcnt lgkmcnt(6)
	v_cvt_pk_bf16_f32 v52, v66, v64
	v_lshlrev_b32_e32 v44, 2, v0
	v_lshrrev_b32_e32 v0, 1, v0
	v_and_b32_e32 v44, 0x90, v44
	v_and_b32_e32 v0, 0x68, v0
	v_bitop3_b32 v45, s6, v43, v20 bitop3:0xc8
	v_or3_b32 v0, v45, v0, v44
	v_lshlrev_b32_e32 v0, 11, v0
	v_lshl_add_u64 v[44:45], v[76:77], 0, v[0:1]
	v_or_b32_e32 v0, s6, v21
	v_lshlrev_b32_e32 v48, 2, v0
	v_lshrrev_b32_e32 v0, 1, v0
	v_and_b32_e32 v48, 0x90, v48
	v_and_b32_e32 v0, 0x6c, v0
	v_bitop3_b32 v49, s6, v43, v21 bitop3:0xc8
	v_or3_b32 v0, v49, v0, v48
	s_waitcnt lgkmcnt(4)
	v_cvt_pk_bf16_f32 v53, v68, v70
	s_waitcnt lgkmcnt(2)
	v_cvt_pk_bf16_f32 v54, v72, v74
	s_waitcnt lgkmcnt(0)
	v_cvt_pk_bf16_f32 v55, v82, v84
	v_lshlrev_b32_e32 v0, 11, v0
	global_store_dwordx4 v[44:45], v[52:55], off sc1
	v_cvt_pk_bf16_f32 v44, v67, v65
	v_cvt_pk_bf16_f32 v45, v69, v71
	v_cvt_pk_bf16_f32 v46, v73, v75
	v_cvt_pk_bf16_f32 v47, v83, v85
	v_lshl_add_u64 v[48:49], v[76:77], 0, v[0:1]
	global_store_dwordx4 v[48:49], v[44:47], off sc1
	s_waitcnt lgkmcnt(0)

; #define LAS __attribute__((address_space(3)))
; __device__ __forceinline__ unsigned cvt_pk_bf16(float lo, float hi) { f32x2_t v = {lo, hi}; bf16x2_t b = __builtin_convertvector(v, bf16x2_t); return __builtin_bit_cast(unsigned, b); }
; __host__ __device__ __forceinline__ int prow(int n) { const int cc = n & 255; return (n & ~255) | (((cc >> 5) & 1) * 128 + (cc >> 6) * 32 + ((cc >> 2) & 1) * 16 + ((cc >> 3) & 3) * 4 + (cc & 3)); }
; __device__ __forceinline__ void p0_transpose_item(const float* W, int K, int N, bf16_t* WT, int ldo, int koff, LAS float* scr, int item, int lane) {
;     const int nblk = N / 32, kb = item / nblk, nb = item % nblk, k0 = 64 * kb, n0 = 32 * nb;
;     f32x4 t[8];
; #pragma unroll
;     for (int i = 0; i < 8; ++i) { const int id = lane + 64 * i; t[i] = __builtin_nontemporal_load((const f32x4*)(W + (size_t)(k0 + (id >> 3)) * N + n0 + 4 * (id & 7))); }
; #pragma unroll
;     for (int i = 0; i < 8; ++i) { const int id = lane + 64 * i; LAS float* d = scr + (id >> 3) * 33 + 4 * (id & 7); d[0] = t[i].x; d[1] = t[i].y; d[2] = t[i].z; d[3] = t[i].w; }
;     asm volatile("s_waitcnt lgkmcnt(0)" ::: "memory");
;     const int c = lane & 7;
; #pragma unroll
;     for (int j = 0; j < 4; ++j) { const int n = (lane >> 3) + 8 * j; const LAS float* s = scr + (8 * c) * 33 + n;
;         u32x4 o; o.x = cvt_pk_bf16(s[0 * 33], s[1 * 33]); o.y = cvt_pk_bf16(s[2 * 33], s[3 * 33]); o.z = cvt_pk_bf16(s[4 * 33], s[5 * 33]); o.w = cvt_pk_bf16(s[6 * 33], s[7 * 33]);
;         *(u32x4*)(WT + (size_t)prow(n0 + n) * ldo + koff + k0 + 8 * c) = o; }
;     asm volatile("s_waitcnt lgkmcnt(0)" ::: "memory");
; }
; template <bool COOP>
; __global__ void __launch_bounds__(512, 2) mega(Args a) {
;     ...
;         for (int it = gw; it < NITEMS; it += NGW) {
;             int r = it;
;             if (r < I_IN) { p0_transpose_item(w_in, DM, NIN, WinT, DM, 0, scr, r, lane); continue; } r -= I_IN;
.LBB0_33:
	s_andn2_b64 vcc, exec, s[6:7]
	s_cbranch_vccnz .LBB0_22
	s_mul_hi_i32 s6, s19, 0x2aaaaaab
	s_lshr_b32 s7, s6, 31
	s_ashr_i32 s6, s6, 5
	s_add_i32 s7, s6, s7
	s_mul_i32 s10, s7, 0xffffe800
	s_add_i32 s20, s5, s10
	s_lshl_b32 s6, s7, 6
	s_ashr_i32 s21, s20, 31
	v_lshl_add_u64 v[72:73], s[20:21], 2, v[14:15]
	v_or_b32_e32 v0, s6, v18
	v_mad_i64_i32 v[44:45], s[24:25], v0, s18, v[72:73]
	v_or_b32_e32 v0, s6, v19
	v_mad_i64_i32 v[48:49], s[24:25], v0, s18, v[72:73]
	v_or_b32_e32 v0, s6, v20
	v_or_b32_e32 v56, s6, v21
	v_mad_i64_i32 v[52:53], s[24:25], v0, s18, v[72:73]
	v_or_b32_e32 v0, s6, v22
	v_or_b32_e32 v58, s6, v23
	v_or_b32_e32 v66, s6, v24
	v_mad_i64_i32 v[56:57], s[24:25], v56, s18, v[72:73]
	v_mad_i64_i32 v[60:61], s[24:25], v0, s18, v[72:73]
	v_mad_i64_i32 v[64:65], s[24:25], v58, s18, v[72:73]
	v_mad_i64_i32 v[68:69], s[24:25], v66, s18, v[72:73]
	global_load_dwordx4 v[44:47], v[44:45], off nt
	s_nop 0
	global_load_dwordx4 v[48:51], v[48:49], off nt
	v_or_b32_e32 v74, s6, v25
	global_load_dwordx4 v[52:55], v[52:53], off nt
	s_nop 0
	global_load_dwordx4 v[56:59], v[56:57], off nt
	s_nop 0
	global_load_dwordx4 v[60:63], v[60:61], off nt
	s_nop 0
	global_load_dwordx4 v[64:67], v[64:65], off nt
	s_nop 0
	global_load_dwordx4 v[68:71], v[68:69], off nt
	v_mad_i64_i32 v[72:73], s[24:25], v74, s18, v[72:73]
	global_load_dwordx4 v[72:75], v[72:73], off nt
	s_mul_i32 s10, s7, 0xffffa000
	s_ashr_i32 s7, s6, 31
	v_add_u32_e32 v0, s10, v27
	v_lshl_add_u64 v[76:77], s[6:7], 1, v[16:17]
	v_add_u32_e32 v82, s20, v18
	s_lshr_b32 s6, s20, 1
	v_and_b32_e32 v78, 0x90, v0
	s_and_b32 s6, s6, 0x60
	v_and_b32_e32 v80, 0xffffff03, v82
	v_add_u32_e32 v81, 8, v82
	v_add_u32_e32 v79, 32, v0
	v_or3_b32 v78, s6, v80, v78
	v_lshrrev_b32_e32 v80, 1, v81
	v_and_b32_e32 v83, 0x90, v79
	v_and_b32_e32 v81, 0xffffff03, v81
	v_and_b32_e32 v80, 0x64, v80
	v_ashrrev_i32_e32 v79, 31, v78
	v_or3_b32 v80, v80, v81, v83
	v_lshlrev_b64 v[78:79], 11, v[78:79]
	v_ashrrev_i32_e32 v81, 31, v80
	v_lshl_add_u64 v[78:79], v[76:77], 0, v[78:79]
	s_waitcnt vmcnt(7)
	ds_write2_b32 v28, v44, v45 offset1:1
	ds_write2_b32 v28, v46, v47 offset0:2 offset1:3
	s_waitcnt vmcnt(6)
	ds_write2_b32 v29, v48, v49 offset1:1
	ds_write2_b32 v30, v50, v51 offset1:1
	s_waitcnt vmcnt(5)
	ds_write2_b32 v31, v52, v53 offset1:1
	ds_write2_b32 v32, v54, v55 offset1:1
	s_waitcnt vmcnt(4)
	ds_write2_b32 v33, v56, v57 offset1:1
	ds_write2_b32 v34, v58, v59 offset1:1
	s_waitcnt vmcnt(3)
	ds_write2_b32 v35, v60, v61 offset1:1
	ds_write2_b32 v36, v62, v63 offset1:1
	s_waitcnt vmcnt(2)
	ds_write2_b32 v37, v64, v65 offset1:1
	ds_write2_b32 v38, v66, v67 offset1:1
	s_waitcnt vmcnt(1)
	ds_write2_b32 v39, v68, v69 offset1:1
	ds_write2_b32 v40, v70, v71 offset1:1
	s_waitcnt vmcnt(0)
	ds_write2_b32 v41, v72, v73 offset1:1
	ds_write2_b32 v42, v74, v75 offset1:1
	s_waitcnt lgkmcnt(0)
	ds_read2_b32 v[48:49], v26 offset0:33 offset1:41
	ds_read2_b32 v[50:51], v26 offset1:8
	ds_read2_b32 v[52:53], v26 offset0:66 offset1:74
	ds_read2_b32 v[54:55], v26 offset0:99 offset1:107
	ds_read2_b32 v[56:57], v26 offset0:132 offset1:140
	ds_read2_b32 v[58:59], v26 offset0:165 offset1:173
	ds_read2_b32 v[60:61], v26 offset0:198 offset1:206
	ds_read2_b32 v[62:63], v26 offset0:231 offset1:239
	v_lshlrev_b64 v[64:65], 11, v[80:81]
	s_waitcnt lgkmcnt(6)
	v_cvt_pk_bf16_f32 v44, v50, v48
	s_waitcnt lgkmcnt(4)
	v_cvt_pk_bf16_f32 v45, v52, v54
	s_waitcnt lgkmcnt(2)
	v_cvt_pk_bf16_f32 v46, v56, v58
	s_waitcnt lgkmcnt(0)
	v_cvt_pk_bf16_f32 v47, v60, v62
	v_cvt_pk_bf16_f32 v48, v51, v49
	v_cvt_pk_bf16_f32 v49, v53, v55
	v_cvt_pk_bf16_f32 v50, v57, v59
	v_cvt_pk_bf16_f32 v51, v61, v63
	global_store_dwordx4 v[78:79], v[44:47], off sc1
	s_nop 1
	v_lshl_add_u64 v[44:45], v[76:77], 0, v[64:65]
	ds_read2_b32 v[52:53], v26 offset0:16 offset1:24
	ds_read2_b32 v[54:55], v26 offset0:49 offset1:57
	ds_read2_b32 v[56:57], v26 offset0:82 offset1:90
	ds_read2_b32 v[58:59], v26 offset0:115 offset1:123
	ds_read2_b32 v[60:61], v26 offset0:148 offset1:156
	ds_read2_b32 v[62:63], v26 offset0:181 offset1:189
	ds_read2_b32 v[64:65], v26 offset0:214 offset1:222
	ds_read2_b32 v[66:67], v26 offset0:247 offset1:255
	global_store_dwordx4 v[44:45], v[48:51], off sc1
	s_waitcnt lgkmcnt(6)
	v_cvt_pk_bf16_f32 v44, v52, v54
	s_waitcnt lgkmcnt(4)
	v_cvt_pk_bf16_f32 v45, v56, v58
	v_add_u32_e32 v48, 16, v82
	v_add_u32_e32 v49, 64, v0
	v_lshrrev_b32_e32 v50, 1, v48
	v_and_b32_e32 v49, 0x90, v49
	v_and_b32_e32 v50, 0x68, v50
	v_and_b32_e32 v48, 0xffffff03, v48
	v_or3_b32 v48, v50, v48, v49
	v_ashrrev_i32_e32 v49, 31, v48
	v_lshlrev_b64 v[48:49], 11, v[48:49]
	s_waitcnt lgkmcnt(2)
	v_cvt_pk_bf16_f32 v46, v60, v62
	s_waitcnt lgkmcnt(0)
	v_cvt_pk_bf16_f32 v47, v64, v66
	v_lshl_add_u64 v[48:49], v[76:77], 0, v[48:49]
	global_store_dwordx4 v[48:49], v[44:47], off sc1
	v_add_u32_e32 v48, 24, v82
	v_add_u32_e32 v0, 0x60, v0
	v_lshrrev_b32_e32 v49, 1, v48
	v_and_b32_e32 v0, 0x90, v0
	v_and_b32_e32 v49, 0x6c, v49
	v_and_b32_e32 v48, 0xffffff03, v48
	v_or3_b32 v48, v49, v48, v0
	v_ashrrev_i32_e32 v49, 31, v48
	v_lshlrev_b64 v[48:49], 11, v[48:49]
	v_cvt_pk_bf16_f32 v44, v53, v55
	v_cvt_pk_bf16_f32 v45, v57, v59
	v_cvt_pk_bf16_f32 v46, v61, v63
	v_cvt_pk_bf16_f32 v47, v65, v67
	v_lshl_add_u64 v[48:49], v[76:77], 0, v[48:49]
	global_store_dwordx4 v[48:49], v[44:47], off sc1
	s_waitcnt lgkmcnt(0)
	s_branch .LBB0_22

; __device__ __forceinline__ unsigned cvt_pk_bf16(float lo, float hi) { f32x2_t v = {lo, hi}; bf16x2_t b = __builtin_convertvector(v, bf16x2_t); return __builtin_bit_cast(unsigned, b); }
; __device__ __forceinline__ void rms_rows4_to_bf16(const float* xp, const float* xs, const float* nw, bf16_t* XN, int m, int step, int lane) {
;     f32x4 v[4][4];
; #pragma unroll
;     for (int r = 0; r < 4; ++r) { const int mr = m + r * step;
;         if (mr < MT) { const f32x4* xr = (const f32x4*)(mr < MP ? xp + (size_t)mr * DM : xs + (size_t)(mr - MP) * DM) + lane;
; #pragma unroll
;             for (int j = 0; j < 4; ++j) v[r][j] = __builtin_nontemporal_load(xr + 64 * j); } }
;     f32x4 w[4];
; #pragma unroll
;     for (int j = 0; j < 4; ++j) w[j] = ((const f32x4*)nw + lane)[64 * j];
; #pragma unroll
;     for (int r = 0; r < 4; ++r) { const int mr = m + r * step;
;         if (mr < MT) { float s = 0.f;
; #pragma unroll
;             for (int j = 0; j < 4; ++j) s += (v[r][j].x * v[r][j].x + v[r][j].y * v[r][j].y) + (v[r][j].z * v[r][j].z + v[r][j].w * v[r][j].w);
;             const float rinv = __builtin_amdgcn_rsqf(wave_sum(s) * (1.f / DM) + EPS);
;             u32x2* o8 = (u32x2*)(XN + (size_t)mr * DM) + lane;
; #pragma unroll
;             for (int j = 0; j < 4; ++j) { const f32x4 y = v[r][j] * rinv * w[j]; u32x2 o; o.x = cvt_pk_bf16(y.x, y.y); o.y = cvt_pk_bf16(y.z, y.w); o8[64 * j] = o; } } }
; }
.LBB0_44:
	global_load_dwordx4 v[52:55], v[80:81], off
	global_load_dwordx4 v[48:51], v[80:81], off offset:1024
	global_load_dwordx4 v[36:39], v[80:81], off offset:2048
	global_load_dwordx4 v[24:27], v[80:81], off offset:3072
	s_waitcnt vmcnt(7)
	v_pk_mul_f32 v[92:93], v[78:79], v[78:79]
	v_pk_mul_f32 v[94:95], v[76:77], v[76:77]
	s_lshl_b64 s[4:5], s[4:5], 11
	v_pk_mov_b32 v[96:97], v[94:95], v[92:93] op_sel:[1,0]
	v_mov_b32_e32 v95, v93
	v_pk_add_f32 v[92:93], v[96:97], v[94:95]
	s_waitcnt vmcnt(6)
	v_pk_mul_f32 v[94:95], v[74:75], v[74:75]
	v_pk_mul_f32 v[96:97], v[72:73], v[72:73]
	v_pk_add_f32 v[92:93], v[92:93], v[92:93] op_sel:[0,1] op_sel_hi:[1,0]
	v_pk_mov_b32 v[98:99], v[96:97], v[94:95] op_sel:[1,0]
	v_mov_b32_e32 v97, v95
	v_pk_add_f32 v[94:95], v[98:99], v[96:97]
	s_waitcnt vmcnt(4)
	v_mul_f32_e32 v96, v64, v64
	v_mul_f32_e32 v97, v65, v65
	v_pk_add_f32 v[94:95], v[94:95], v[94:95] op_sel:[0,1] op_sel_hi:[1,0]
	v_mov_b32_e32 v93, v96
	v_mov_b32_e32 v95, v97
	v_pk_add_f32 v[92:93], v[92:93], v[94:95]
	v_mul_f32_e32 v94, v69, v69
	v_mul_f32_e32 v96, v71, v71
	v_mul_f32_e32 v98, v66, v66
	v_mul_f32_e32 v99, v67, v67
	v_pk_fma_f32 v[94:95], v[68:69], v[68:69], v[94:95] op_sel_hi:[1,1,0]
	v_pk_fma_f32 v[96:97], v[70:71], v[70:71], v[96:97] op_sel_hi:[1,1,0]
	v_mov_b32_e32 v95, v98
	v_mov_b32_e32 v97, v99
	v_pk_add_f32 v[94:95], v[94:95], v[96:97]
	s_andn2_b64 vcc, exec, s[20:21]
	v_pk_add_f32 v[92:93], v[92:93], v[94:95]
	v_lshl_add_u64 v[94:95], v[82:83], 0, s[4:5]
	v_add_f32_e32 v92, v92, v93
	ds_bpermute_b32 v93, v84, v92
	s_waitcnt lgkmcnt(0)
	v_add_f32_e32 v92, v92, v93
	ds_bpermute_b32 v93, v85, v92
	s_waitcnt lgkmcnt(0)
	v_add_f32_e32 v92, v92, v93
	ds_bpermute_b32 v93, v86, v92
	s_waitcnt lgkmcnt(0)
	v_add_f32_e32 v92, v92, v93
	ds_bpermute_b32 v93, v87, v92
	s_waitcnt lgkmcnt(0)
	v_add_f32_e32 v92, v92, v93
	ds_bpermute_b32 v93, v88, v92
	s_waitcnt lgkmcnt(0)
	v_add_f32_e32 v92, v92, v93
	ds_bpermute_b32 v93, v89, v92
	s_waitcnt lgkmcnt(0)
	v_add_f32_e32 v92, v92, v93
	v_fmamk_f32 v92, v92, 0x3a800000, v91
	v_rsq_f32_e32 v92, v92
	s_nop 0
	v_pk_mul_f32 v[76:77], v[76:77], v[92:93] op_sel_hi:[1,0]
	v_pk_mul_f32 v[78:79], v[78:79], v[92:93] op_sel_hi:[1,0]
	v_pk_mul_f32 v[72:73], v[72:73], v[92:93] op_sel_hi:[1,0]
	v_pk_mul_f32 v[74:75], v[74:75], v[92:93] op_sel_hi:[1,0]
	v_pk_mul_f32 v[68:69], v[68:69], v[92:93] op_sel_hi:[1,0]
	v_pk_mul_f32 v[70:71], v[70:71], v[92:93] op_sel_hi:[1,0]
	v_pk_mul_f32 v[64:65], v[64:65], v[92:93] op_sel_hi:[1,0]
	v_pk_mul_f32 v[66:67], v[66:67], v[92:93] op_sel_hi:[1,0]
	s_waitcnt vmcnt(3)
	v_pk_mul_f32 v[78:79], v[54:55], v[78:79]
	v_pk_mul_f32 v[76:77], v[52:53], v[76:77]
	s_waitcnt vmcnt(2)
	v_pk_mul_f32 v[74:75], v[50:51], v[74:75]
	v_pk_mul_f32 v[72:73], v[48:49], v[72:73]
	s_waitcnt vmcnt(1)
	v_pk_mul_f32 v[70:71], v[38:39], v[70:71]
	v_pk_mul_f32 v[68:69], v[36:37], v[68:69]
	s_waitcnt vmcnt(0)
	v_pk_mul_f32 v[66:67], v[26:27], v[66:67]
	v_pk_mul_f32 v[64:65], v[24:25], v[64:65]
	v_cvt_pk_bf16_f32 v76, v76, v77
	v_cvt_pk_bf16_f32 v77, v78, v79
	v_cvt_pk_bf16_f32 v72, v72, v73
	v_cvt_pk_bf16_f32 v73, v74, v75
	v_cvt_pk_bf16_f32 v68, v68, v69
	v_cvt_pk_bf16_f32 v69, v70, v71
	v_cvt_pk_bf16_f32 v64, v64, v65
	v_cvt_pk_bf16_f32 v65, v66, v67
	global_store_dwordx2 v[94:95], v[76:77], off sc1
	global_store_dwordx2 v[94:95], v[72:73], off offset:512 sc1
	global_store_dwordx2 v[94:95], v[68:69], off offset:1024 sc1
	global_store_dwordx2 v[94:95], v[64:65], off offset:1536 sc1
	s_cbranch_vccnz .LBB0_47
	v_pk_mul_f32 v[64:65], v[62:63], v[62:63]
	v_pk_mul_f32 v[66:67], v[60:61], v[60:61]
	s_ashr_i32 s11, s10, 31
	v_pk_mov_b32 v[68:69], v[66:67], v[64:65] op_sel:[1,0]
	v_mov_b32_e32 v67, v65
	v_pk_add_f32 v[64:65], v[68:69], v[66:67]
	v_pk_mul_f32 v[66:67], v[58:59], v[58:59]
	v_pk_add_f32 v[64:65], v[64:65], v[64:65] op_sel_hi:[0,1]
	v_pk_mul_f32 v[68:69], v[56:57], v[56:57]
	v_mul_f32_e32 v64, v44, v44
	v_pk_mov_b32 v[70:71], v[68:69], v[66:67] op_sel:[1,0]
	v_mov_b32_e32 v69, v67
	v_pk_add_f32 v[66:67], v[70:71], v[68:69]
	v_pk_fma_f32 v[68:69], v[44:45], v[44:45], v[64:65] op_sel_hi:[1,1,0]
	v_mul_f32_e32 v64, v46, v46
	v_pk_add_f32 v[66:67], v[66:67], v[66:67] op_sel_hi:[0,1]
	v_pk_fma_f32 v[70:71], v[46:47], v[46:47], v[64:65] op_sel_hi:[1,1,0]
	v_mul_f32_e32 v68, v28, v28
	v_mul_f32_e32 v70, v29, v29
	v_mul_f32_e32 v66, v30, v30
	v_mul_f32_e32 v64, v31, v31
	v_pk_add_f32 v[68:69], v[68:69], v[70:71]
	v_pk_add_f32 v[64:65], v[66:67], v[64:65]
	s_lshl_b64 s[4:5], s[10:11], 11
	v_pk_add_f32 v[64:65], v[68:69], v[64:65]
	v_lshl_add_u64 v[66:67], v[82:83], 0, s[4:5]
	v_add_f32_e32 v64, v64, v65
	ds_bpermute_b32 v65, v84, v64
	s_waitcnt lgkmcnt(0)
	v_add_f32_e32 v64, v64, v65
	ds_bpermute_b32 v65, v85, v64
	s_waitcnt lgkmcnt(0)
	v_add_f32_e32 v64, v64, v65
	ds_bpermute_b32 v65, v86, v64
	s_waitcnt lgkmcnt(0)
	v_add_f32_e32 v64, v64, v65
	ds_bpermute_b32 v65, v87, v64
	s_waitcnt lgkmcnt(0)
	v_add_f32_e32 v64, v64, v65
	ds_bpermute_b32 v65, v88, v64
	s_waitcnt lgkmcnt(0)
	v_add_f32_e32 v64, v64, v65
	ds_bpermute_b32 v65, v89, v64
	s_waitcnt lgkmcnt(0)
	v_add_f32_e32 v64, v64, v65
	v_fmamk_f32 v64, v64, 0x3a800000, v91
	v_rsq_f32_e32 v64, v64
	s_nop 0
	v_pk_mul_f32 v[60:61], v[60:61], v[64:65] op_sel_hi:[1,0]
	v_pk_mul_f32 v[62:63], v[62:63], v[64:65] op_sel_hi:[1,0]
	v_pk_mul_f32 v[56:57], v[56:57], v[64:65] op_sel_hi:[1,0]
	v_pk_mul_f32 v[58:59], v[58:59], v[64:65] op_sel_hi:[1,0]
	v_pk_mul_f32 v[44:45], v[44:45], v[64:65] op_sel_hi:[1,0]
	v_pk_mul_f32 v[46:47], v[46:47], v[64:65] op_sel_hi:[1,0]
	v_pk_mul_f32 v[28:29], v[28:29], v[64:65] op_sel_hi:[1,0]
	v_pk_mul_f32 v[30:31], v[30:31], v[64:65] op_sel_hi:[1,0]
	v_pk_mul_f32 v[62:63], v[54:55], v[62:63]
	v_pk_mul_f32 v[60:61], v[52:53], v[60:61]
	v_pk_mul_f32 v[58:59], v[50:51], v[58:59]
	v_pk_mul_f32 v[56:57], v[48:49], v[56:57]
	v_pk_mul_f32 v[46:47], v[38:39], v[46:47]
	v_pk_mul_f32 v[44:45], v[36:37], v[44:45]
	v_pk_mul_f32 v[30:31], v[26:27], v[30:31]
	v_pk_mul_f32 v[28:29], v[24:25], v[28:29]
	v_cvt_pk_bf16_f32 v60, v60, v61
	v_cvt_pk_bf16_f32 v61, v62, v63
	v_cvt_pk_bf16_f32 v56, v56, v57
	v_cvt_pk_bf16_f32 v57, v58, v59
	v_cvt_pk_bf16_f32 v44, v44, v45
	v_cvt_pk_bf16_f32 v45, v46, v47
	v_cvt_pk_bf16_f32 v28, v28, v29
	v_cvt_pk_bf16_f32 v29, v30, v31
	global_store_dwordx2 v[66:67], v[60:61], off sc1
	global_store_dwordx2 v[66:67], v[56:57], off offset:512 sc1
	global_store_dwordx2 v[66:67], v[44:45], off offset:1024 sc1
	global_store_dwordx2 v[66:67], v[28:29], off offset:1536 sc1
	s_andn2_b64 vcc, exec, s[18:19]
	s_cbranch_vccz .LBB0_48

; __device__ __forceinline__ unsigned cvt_pk_bf16(float lo, float hi) { f32x2_t v = {lo, hi}; bf16x2_t b = __builtin_convertvector(v, bf16x2_t); return __builtin_bit_cast(unsigned, b); }
; __device__ __forceinline__ void rms_rows4_to_bf16(const float* xp, const float* xs, const float* nw, bf16_t* XN, int m, int step, int lane) {
;     f32x4 v[4][4];
; #pragma unroll
;     for (int r = 0; r < 4; ++r) { const int mr = m + r * step;
;         if (mr < MT) { const f32x4* xr = (const f32x4*)(mr < MP ? xp + (size_t)mr * DM : xs + (size_t)(mr - MP) * DM) + lane;
; #pragma unroll
;             for (int j = 0; j < 4; ++j) v[r][j] = __builtin_nontemporal_load(xr + 64 * j); } }
;     f32x4 w[4];
; #pragma unroll
;     for (int j = 0; j < 4; ++j) w[j] = ((const f32x4*)nw + lane)[64 * j];
; #pragma unroll
;     for (int r = 0; r < 4; ++r) { const int mr = m + r * step;
;         if (mr < MT) { float s = 0.f;
; #pragma unroll
;             for (int j = 0; j < 4; ++j) s += (v[r][j].x * v[r][j].x + v[r][j].y * v[r][j].y) + (v[r][j].z * v[r][j].z + v[r][j].w * v[r][j].w);
;             const float rinv = __builtin_amdgcn_rsqf(wave_sum(s) * (1.f / DM) + EPS);
;             u32x2* o8 = (u32x2*)(XN + (size_t)mr * DM) + lane;
; #pragma unroll
;             for (int j = 0; j < 4; ++j) { const f32x4 y = v[r][j] * rinv * w[j]; u32x2 o; o.x = cvt_pk_bf16(y.x, y.y); o.y = cvt_pk_bf16(y.z, y.w); o8[64 * j] = o; } } }
; }
.LBB0_48:
	v_pk_mul_f32 v[28:29], v[42:43], v[42:43]
	v_pk_mul_f32 v[30:31], v[40:41], v[40:41]
	s_ashr_i32 s15, s14, 31
	v_pk_mov_b32 v[44:45], v[30:31], v[28:29] op_sel:[1,0]
	v_mov_b32_e32 v31, v29
	v_pk_add_f32 v[28:29], v[44:45], v[30:31]
	v_pk_mul_f32 v[30:31], v[34:35], v[34:35]
	v_pk_add_f32 v[28:29], v[28:29], v[28:29] op_sel_hi:[0,1]
	v_pk_mul_f32 v[44:45], v[32:33], v[32:33]
	v_mul_f32_e32 v28, v20, v20
	v_pk_mov_b32 v[46:47], v[44:45], v[30:31] op_sel:[1,0]
	v_mov_b32_e32 v45, v31
	v_pk_add_f32 v[30:31], v[46:47], v[44:45]
	v_pk_fma_f32 v[44:45], v[20:21], v[20:21], v[28:29] op_sel_hi:[1,1,0]
	v_mul_f32_e32 v28, v22, v22
	v_pk_add_f32 v[30:31], v[30:31], v[30:31] op_sel_hi:[0,1]
	v_pk_fma_f32 v[46:47], v[22:23], v[22:23], v[28:29] op_sel_hi:[1,1,0]
	v_mul_f32_e32 v44, v12, v12
	v_mul_f32_e32 v46, v13, v13
	v_mul_f32_e32 v30, v14, v14
	v_mul_f32_e32 v28, v15, v15
	v_pk_add_f32 v[44:45], v[44:45], v[46:47]
	v_pk_add_f32 v[28:29], v[30:31], v[28:29]
	s_lshl_b64 s[4:5], s[14:15], 11
	v_pk_add_f32 v[28:29], v[44:45], v[28:29]
	v_lshl_add_u64 v[30:31], v[82:83], 0, s[4:5]
	v_add_f32_e32 v28, v28, v29
	ds_bpermute_b32 v29, v84, v28
	s_waitcnt lgkmcnt(0)
	v_add_f32_e32 v28, v28, v29
	ds_bpermute_b32 v29, v85, v28
	s_waitcnt lgkmcnt(0)
	v_add_f32_e32 v28, v28, v29
	ds_bpermute_b32 v29, v86, v28
	s_waitcnt lgkmcnt(0)
	v_add_f32_e32 v28, v28, v29
	ds_bpermute_b32 v29, v87, v28
	s_waitcnt lgkmcnt(0)
	v_add_f32_e32 v28, v28, v29
	ds_bpermute_b32 v29, v88, v28
	s_waitcnt lgkmcnt(0)
	v_add_f32_e32 v28, v28, v29
	ds_bpermute_b32 v29, v89, v28
	s_waitcnt lgkmcnt(0)
	v_add_f32_e32 v28, v28, v29
	v_fmamk_f32 v28, v28, 0x3a800000, v91
	v_rsq_f32_e32 v28, v28
	s_nop 0
	v_pk_mul_f32 v[40:41], v[40:41], v[28:29] op_sel_hi:[1,0]
	v_pk_mul_f32 v[42:43], v[42:43], v[28:29] op_sel_hi:[1,0]
	v_pk_mul_f32 v[32:33], v[32:33], v[28:29] op_sel_hi:[1,0]
	v_pk_mul_f32 v[34:35], v[34:35], v[28:29] op_sel_hi:[1,0]
	v_pk_mul_f32 v[20:21], v[20:21], v[28:29] op_sel_hi:[1,0]
	v_pk_mul_f32 v[22:23], v[22:23], v[28:29] op_sel_hi:[1,0]
	v_pk_mul_f32 v[12:13], v[12:13], v[28:29] op_sel_hi:[1,0]
	v_pk_mul_f32 v[14:15], v[14:15], v[28:29] op_sel_hi:[1,0]
	v_pk_mul_f32 v[42:43], v[54:55], v[42:43]
	v_pk_mul_f32 v[40:41], v[52:53], v[40:41]
	v_pk_mul_f32 v[34:35], v[50:51], v[34:35]
	v_pk_mul_f32 v[32:33], v[48:49], v[32:33]
	v_pk_mul_f32 v[22:23], v[38:39], v[22:23]
	v_pk_mul_f32 v[20:21], v[36:37], v[20:21]
	v_pk_mul_f32 v[14:15], v[26:27], v[14:15]
	v_pk_mul_f32 v[12:13], v[24:25], v[12:13]
	v_cvt_pk_bf16_f32 v40, v40, v41
	v_cvt_pk_bf16_f32 v41, v42, v43
	v_cvt_pk_bf16_f32 v32, v32, v33
	v_cvt_pk_bf16_f32 v33, v34, v35
	v_cvt_pk_bf16_f32 v20, v20, v21
	v_cvt_pk_bf16_f32 v21, v22, v23
	v_cvt_pk_bf16_f32 v12, v12, v13
	v_cvt_pk_bf16_f32 v13, v14, v15
	global_store_dwordx2 v[30:31], v[40:41], off sc1
	global_store_dwordx2 v[30:31], v[32:33], off offset:512 sc1
	global_store_dwordx2 v[30:31], v[20:21], off offset:1024 sc1
	global_store_dwordx2 v[30:31], v[12:13], off offset:1536 sc1
	s_andn2_b64 vcc, exec, s[16:17]
	s_cbranch_vccnz .LBB0_37
.LBB0_49:
	v_pk_mul_f32 v[12:13], v[18:19], v[18:19]
	v_pk_mul_f32 v[14:15], v[16:17], v[16:17]
	s_ashr_i32 s13, s12, 31
	v_pk_mov_b32 v[20:21], v[14:15], v[12:13] op_sel:[1,0]
	v_mov_b32_e32 v15, v13
	v_pk_add_f32 v[12:13], v[20:21], v[14:15]
	v_pk_mul_f32 v[14:15], v[10:11], v[10:11]
	v_pk_mul_f32 v[20:21], v[8:9], v[8:9]
	v_pk_add_f32 v[12:13], v[12:13], v[12:13] op_sel:[0,1] op_sel_hi:[1,0]
	v_pk_mov_b32 v[22:23], v[20:21], v[14:15] op_sel:[1,0]
	v_mov_b32_e32 v21, v15
	v_pk_add_f32 v[14:15], v[22:23], v[20:21]
	v_mul_f32_e32 v20, v0, v0
	v_mul_f32_e32 v21, v1, v1
	v_pk_add_f32 v[14:15], v[14:15], v[14:15] op_sel:[0,1] op_sel_hi:[1,0]
	v_mov_b32_e32 v13, v20
	v_mov_b32_e32 v15, v21
	v_pk_add_f32 v[12:13], v[12:13], v[14:15]
	v_mul_f32_e32 v14, v5, v5
	v_mul_f32_e32 v20, v7, v7
	v_mul_f32_e32 v22, v2, v2
	v_mul_f32_e32 v23, v3, v3
	v_pk_fma_f32 v[14:15], v[4:5], v[4:5], v[14:15] op_sel_hi:[1,1,0]
	v_pk_fma_f32 v[20:21], v[6:7], v[6:7], v[20:21] op_sel_hi:[1,1,0]
	v_mov_b32_e32 v15, v22
	v_mov_b32_e32 v21, v23
	v_pk_add_f32 v[14:15], v[14:15], v[20:21]
	s_lshl_b64 s[4:5], s[12:13], 11
	v_pk_add_f32 v[12:13], v[12:13], v[14:15]
	v_lshl_add_u64 v[14:15], v[82:83], 0, s[4:5]
	v_add_f32_e32 v12, v12, v13
	ds_bpermute_b32 v13, v84, v12
	s_waitcnt lgkmcnt(0)
	v_add_f32_e32 v12, v12, v13
	ds_bpermute_b32 v13, v85, v12
	s_waitcnt lgkmcnt(0)
	v_add_f32_e32 v12, v12, v13
	ds_bpermute_b32 v13, v86, v12
	s_waitcnt lgkmcnt(0)
	v_add_f32_e32 v12, v12, v13
	ds_bpermute_b32 v13, v87, v12
	s_waitcnt lgkmcnt(0)
	v_add_f32_e32 v12, v12, v13
	ds_bpermute_b32 v13, v88, v12
	s_waitcnt lgkmcnt(0)
	v_add_f32_e32 v12, v12, v13
	ds_bpermute_b32 v13, v89, v12
	s_waitcnt lgkmcnt(0)
	v_add_f32_e32 v12, v12, v13
	v_fmamk_f32 v12, v12, 0x3a800000, v91
	v_rsq_f32_e32 v12, v12
	s_nop 0
	v_pk_mul_f32 v[16:17], v[16:17], v[12:13] op_sel_hi:[1,0]
	v_pk_mul_f32 v[18:19], v[18:19], v[12:13] op_sel_hi:[1,0]
	v_pk_mul_f32 v[8:9], v[8:9], v[12:13] op_sel_hi:[1,0]
	v_pk_mul_f32 v[10:11], v[10:11], v[12:13] op_sel_hi:[1,0]
	v_pk_mul_f32 v[4:5], v[4:5], v[12:13] op_sel_hi:[1,0]
	v_pk_mul_f32 v[6:7], v[6:7], v[12:13] op_sel_hi:[1,0]
	v_pk_mul_f32 v[0:1], v[0:1], v[12:13] op_sel_hi:[1,0]
	v_pk_mul_f32 v[2:3], v[2:3], v[12:13] op_sel_hi:[1,0]
	v_pk_mul_f32 v[18:19], v[54:55], v[18:19]
	v_pk_mul_f32 v[16:17], v[52:53], v[16:17]
	v_pk_mul_f32 v[10:11], v[50:51], v[10:11]
	v_pk_mul_f32 v[8:9], v[48:49], v[8:9]
	v_pk_mul_f32 v[6:7], v[38:39], v[6:7]
	v_pk_mul_f32 v[4:5], v[36:37], v[4:5]
	v_pk_mul_f32 v[2:3], v[26:27], v[2:3]
	v_pk_mul_f32 v[0:1], v[24:25], v[0:1]
	v_cvt_pk_bf16_f32 v16, v16, v17
	v_cvt_pk_bf16_f32 v17, v18, v19
	v_cvt_pk_bf16_f32 v8, v8, v9
	v_cvt_pk_bf16_f32 v9, v10, v11
	v_cvt_pk_bf16_f32 v4, v4, v5
	v_cvt_pk_bf16_f32 v5, v6, v7
	v_cvt_pk_bf16_f32 v0, v0, v1
	v_cvt_pk_bf16_f32 v1, v2, v3
	global_store_dwordx2 v[14:15], v[16:17], off sc1
	global_store_dwordx2 v[14:15], v[8:9], off offset:512 sc1
	global_store_dwordx2 v[14:15], v[4:5], off offset:1024 sc1
	global_store_dwordx2 v[14:15], v[0:1], off offset:1536 sc1
	s_branch .LBB0_37

; #define LAS __attribute__((address_space(3)))
; __device__ __forceinline__ float bf_lo(unsigned u) { return __uint_as_float(u << 16); }
; template <bool GATED>
; __device__ __forceinline__ void sample_gemm(LAS unsigned char* lds, const bf16_t* A, const bf16_t* WT, const bf16_t* GSg, const bf16_t* GCg, bf16_t* Hout,
;                                             const float* xs, float* yout, int j, int wave, int lane, int tid) {
;     ...
;     const int row0 = MP + 32 * (j & 15), col0 = 64 * (j >> 4);
;     const bf16_t* ap = A + (size_t)(row0 + r32) * 1024 + wave * 128 + hi * 8;
;     const bf16_t* bp0 = WT + (size_t)prow(col0 + r32) * 1024 + wave * 128 + hi * 8;
;     const bf16_t* bp1 = WT + (size_t)prow(col0 + 32 + r32) * 1024 + wave * 128 + hi * 8;
;     f32x16 c0 = {}, c1 = {};
; #pragma unroll
;     for (int ks = 0; ks < 8; ++ks) { const bf16x8 a = *(const bf16x8*)(ap + 16 * ks), b0 = *(const bf16x8*)(bp0 + 16 * ks), b1 = *(const bf16x8*)(bp1 + 16 * ks);
;         c0 = __builtin_amdgcn_mfma_f32_32x32x16_bf16(a, b0, c0, 0, 0, 0); c1 = __builtin_amdgcn_mfma_f32_32x32x16_bf16(a, b1, c1, 0, 0, 0); }
;     LAS float* pl = (LAS float*)lds + wave * 2048;
; #pragma unroll
;     for (int r = 0; r < 16; ++r) { const int rr = (r & 3) + 8 * (r >> 2) + 4 * hi; pl[rr * 64 + r32] = c0[r]; pl[rr * 64 + 32 + r32] = c1[r]; }
;     __syncthreads();
;     { const int row = tid >> 4, cq = (tid & 15) * 4; const LAS float* q = (const LAS float*)lds + row * 64 + cq;
;       f32x4 sb = *(const LAS f32x4*)(q) + *(const LAS f32x4*)(q + 2048) + *(const LAS f32x4*)(q + 4096) + *(const LAS f32x4*)(q + 6144);
;       f32x4 cb = *(const LAS f32x4*)(q + 8192) + *(const LAS f32x4*)(q + 10240) + *(const LAS f32x4*)(q + 12288) + *(const LAS f32x4*)(q + 14336);
;       const size_t off = (size_t)(row0 + row) * 1024 + col0 + cq;
;       if (GATED) { const u32x2 a = *(const u32x2*)(GSg + off), c = *(const u32x2*)(GCg + off);
;           u32x2 w; w.x = cvt_pk_bf16(sb[0] * bf_lo(a.x) + cb[0] * bf_lo(c.x), sb[1] * bf_hi(a.x) + cb[1] * bf_hi(c.x)); w.y = cvt_pk_bf16(sb[2] * bf_lo(a.y) + cb[2] * bf_lo(c.y), sb[3] * bf_hi(a.y) + cb[3] * bf_hi(c.y));
;           *(u32x2*)(Hout + off) = w; }
;       else { const f32x4 x = *(const f32x4*)(xs + off - (size_t)MP * 1024); *(f32x4*)(yout + off) = x + sb + cb; } }
;     __syncthreads();
.LBB0_497:
	s_and_b32 s13, s8, 0x1e0
	s_and_b32 s6, s10, 0xffffffc0
	s_bitset1_b32 s13, 15
	v_or_b32_e32 v0, s6, v40
	v_or_b32_e32 v1, s6, v39
	v_or_b32_e32 v4, s13, v40
	v_lshrrev_b32_e32 v0, 1, v0
	v_bitop3_b32 v2, s6, v62, v40 bitop3:0xc8
	v_lshrrev_b32_e32 v1, 1, v1
	v_lshlrev_b32_e32 v32, 11, v4
	v_and_b32_e32 v4, 0x6c, v0
	v_bitop3_b32 v3, s6, v62, v39 bitop3:0xc8
	v_and_b32_e32 v5, 0x6c, v1
	v_or3_b32 v2, v2, v4, v41
	v_lshl_add_u64 v[0:1], v[34:35], 0, v[32:33]
	v_or3_b32 v4, v3, v5, v61
	v_ashrrev_i32_e32 v3, 31, v2
	v_ashrrev_i32_e32 v5, 31, v4
	global_load_dwordx4 v[16:19], v[0:1], off
	global_load_dwordx4 v[64:67], v[0:1], off offset:32
	global_load_dwordx4 v[68:71], v[0:1], off offset:64
	global_load_dwordx4 v[72:75], v[0:1], off offset:96
	global_load_dwordx4 v[76:79], v[0:1], off offset:128
	global_load_dwordx4 v[80:83], v[0:1], off offset:160
	global_load_dwordx4 v[84:87], v[0:1], off offset:192
	global_load_dwordx4 v[88:91], v[0:1], off offset:224
	v_lshlrev_b64 v[0:1], 11, v[2:3]
	v_lshlrev_b64 v[2:3], 11, v[4:5]
	v_lshl_add_u64 v[104:105], v[36:37], 0, v[0:1]
	v_lshl_add_u64 v[106:107], v[36:37], 0, v[2:3]
	global_load_dwordx4 v[0:3], v[104:105], off
	global_load_dwordx4 v[20:23], v[106:107], off
	global_load_dwordx4 v[92:95], v[104:105], off offset:32
	global_load_dwordx4 v[96:99], v[106:107], off offset:32
	global_load_dwordx4 v[100:103], v[104:105], off offset:64
	s_ashr_i32 s7, s6, 31
	s_add_i32 s12, s12, s3
	s_add_i32 s8, s8, s9
	s_add_i32 s10, s10, s11
	s_cmpk_gt_i32 s12, 0xff
	s_waitcnt vmcnt(0)
	v_mfma_f32_32x32x16_bf16 v[0:15], v[16:19], v[0:3], 0
	v_mfma_f32_32x32x16_bf16 v[16:31], v[16:19], v[20:23], 0
	v_mfma_f32_32x32x16_bf16 v[0:15], v[64:67], v[92:95], v[0:15]
	global_load_dwordx4 v[92:95], v[106:107], off offset:64
	v_mfma_f32_32x32x16_bf16 v[16:31], v[64:67], v[96:99], v[16:31]
	global_load_dwordx4 v[64:67], v[104:105], off offset:96
	global_load_dwordx4 v[96:99], v[106:107], off offset:96
	v_mfma_f32_32x32x16_bf16 v[0:15], v[68:71], v[100:103], v[0:15]
	s_waitcnt vmcnt(2)
	v_mfma_f32_32x32x16_bf16 v[16:31], v[68:71], v[92:95], v[16:31]
	global_load_dwordx4 v[68:71], v[104:105], off offset:128
	s_waitcnt vmcnt(2)
	v_mfma_f32_32x32x16_bf16 v[0:15], v[72:75], v[64:67], v[0:15]
	global_load_dwordx4 v[64:67], v[106:107], off offset:128
	s_waitcnt vmcnt(2)
	v_mfma_f32_32x32x16_bf16 v[16:31], v[72:75], v[96:99], v[16:31]
	global_load_dwordx4 v[72:75], v[104:105], off offset:160
	s_waitcnt vmcnt(2)
	v_mfma_f32_32x32x16_bf16 v[0:15], v[76:79], v[68:71], v[0:15]
	global_load_dwordx4 v[68:71], v[106:107], off offset:160
	s_waitcnt vmcnt(2)
	v_mfma_f32_32x32x16_bf16 v[16:31], v[76:79], v[64:67], v[16:31]
	global_load_dwordx4 v[64:67], v[104:105], off offset:192
	s_waitcnt vmcnt(2)
	v_mfma_f32_32x32x16_bf16 v[0:15], v[80:83], v[72:75], v[0:15]
	global_load_dwordx4 v[72:75], v[106:107], off offset:192
	s_waitcnt vmcnt(2)
	v_mfma_f32_32x32x16_bf16 v[16:31], v[80:83], v[68:71], v[16:31]
	global_load_dwordx4 v[68:71], v[104:105], off offset:224
	s_waitcnt vmcnt(2)
	v_mfma_f32_32x32x16_bf16 v[0:15], v[84:87], v[64:67], v[0:15]
	global_load_dwordx4 v[64:67], v[106:107], off offset:224
	s_waitcnt vmcnt(2)
	v_mfma_f32_32x32x16_bf16 v[16:31], v[84:87], v[72:75], v[16:31]
	v_add_u32_e32 v72, s13, v59
	v_ashrrev_i32_e32 v73, 31, v72
	s_waitcnt vmcnt(1)
	v_mfma_f32_32x32x16_bf16 v[0:15], v[88:91], v[68:71], v[0:15]
	v_lshlrev_b64 v[68:69], 10, v[72:73]
	v_lshl_add_u64 v[68:69], v[68:69], 0, s[6:7]
	v_or_b32_e32 v68, v68, v38
	v_lshlrev_b64 v[68:69], 1, v[68:69]
	v_lshl_add_u64 v[70:71], s[56:57], 0, v[68:69]
	v_lshl_add_u64 v[72:73], s[4:5], 0, v[68:69]
	v_lshl_add_u64 v[68:69], s[58:59], 0, v[68:69]
	s_waitcnt vmcnt(0)
	v_mfma_f32_32x32x16_bf16 v[16:31], v[88:91], v[64:67], v[16:31]
	s_nop 2
	ds_write_b32 v42, v0
	s_nop 7
	ds_write_b32 v43, v16
	ds_write_b32 v42, v1 offset:256
	ds_write_b32 v44, v17
	ds_write_b32 v42, v2 offset:512
	ds_write_b32 v45, v18
	ds_write_b32 v42, v3 offset:768
	ds_write_b32 v46, v19
	ds_write_b32 v42, v4 offset:2048
	ds_write_b32 v47, v20
	ds_write_b32 v42, v5 offset:2304
	ds_write_b32 v48, v21
	ds_write_b32 v42, v6 offset:2560
	ds_write_b32 v49, v22
	ds_write_b32 v42, v7 offset:2816
	ds_write_b32 v50, v23
	ds_write_b32 v42, v8 offset:4096
	ds_write_b32 v51, v24
	ds_write_b32 v42, v9 offset:4352
	ds_write_b32 v52, v25
	ds_write_b32 v42, v10 offset:4608
	ds_write_b32 v53, v26
	ds_write_b32 v42, v11 offset:4864
	ds_write_b32 v54, v27
	ds_write_b32 v42, v12 offset:6144
	ds_write_b32 v55, v28
	ds_write_b32 v42, v13 offset:6400
	ds_write_b32 v56, v29
	ds_write_b32 v42, v14 offset:6656
	ds_write_b32 v57, v30
	ds_write_b32 v42, v15 offset:6912
	ds_write_b32 v58, v31
	s_waitcnt lgkmcnt(0)
	s_barrier
	global_load_dwordx2 v[64:65], v[70:71], off
	global_load_dwordx2 v[66:67], v[72:73], off
	ds_read_b128 v[0:3], v60
	ds_read_b128 v[4:7], v60 offset:8192
	ds_read_b128 v[8:11], v60 offset:16384
	ds_read_b128 v[12:15], v60 offset:24576
	ds_read_b128 v[16:19], v60 offset:32768
	ds_read_b128 v[20:23], v60 offset:40960
	ds_read_b128 v[24:27], v60 offset:49152
	ds_read_b128 v[28:31], v60 offset:57344
	s_waitcnt lgkmcnt(6)
	v_pk_add_f32 v[2:3], v[2:3], v[6:7]
	v_pk_add_f32 v[0:1], v[0:1], v[4:5]
	s_waitcnt lgkmcnt(2)
	v_pk_add_f32 v[4:5], v[18:19], v[22:23]
	v_pk_add_f32 v[6:7], v[16:17], v[20:21]
	v_pk_add_f32 v[2:3], v[2:3], v[10:11]
	s_waitcnt lgkmcnt(1)
	v_pk_add_f32 v[4:5], v[4:5], v[26:27]
	v_pk_add_f32 v[6:7], v[6:7], v[24:25]
	v_pk_add_f32 v[0:1], v[0:1], v[8:9]
	v_pk_add_f32 v[2:3], v[2:3], v[14:15]
	s_waitcnt lgkmcnt(0)
	v_pk_add_f32 v[4:5], v[4:5], v[30:31]
	v_pk_add_f32 v[6:7], v[6:7], v[28:29]
	v_pk_add_f32 v[0:1], v[0:1], v[12:13]
	s_waitcnt vmcnt(1)
	v_lshlrev_b32_e32 v8, 16, v64
	s_waitcnt vmcnt(0)
	v_lshlrev_b32_e32 v10, 16, v66
	v_and_b32_e32 v11, 0xffff0000, v66
	v_lshlrev_b32_e32 v14, 16, v67
	v_and_b32_e32 v15, 0xffff0000, v67
	v_and_b32_e32 v9, 0xffff0000, v64
	v_lshlrev_b32_e32 v12, 16, v65
	v_and_b32_e32 v13, 0xffff0000, v65
	v_pk_mul_f32 v[6:7], v[6:7], v[10:11]
	v_pk_mul_f32 v[4:5], v[4:5], v[14:15]
	v_pk_fma_f32 v[0:1], v[0:1], v[8:9], v[6:7]
	v_pk_fma_f32 v[2:3], v[2:3], v[12:13], v[4:5]
	v_cvt_pk_bf16_f32 v0, v0, v1
	v_cvt_pk_bf16_f32 v1, v2, v3
	global_store_dwordx2 v[68:69], v[0:1], off sc1
	s_barrier
	s_cbranch_scc0 .LBB0_497

; __device__ __forceinline__ float bf_lo(unsigned u) { return __uint_as_float(u << 16); }
; __device__ __forceinline__ float bf_hi(unsigned u) { return __uint_as_float(u & 0xffff0000u); }
; __device__ __forceinline__ u32x4 pack8(f32x4 a, f32x4 b) { u32x4 w; w.x = cvt_pk_bf16(a[0], a[1]); w.y = cvt_pk_bf16(a[2], a[3]); w.z = cvt_pk_bf16(b[0], b[1]); w.w = cvt_pk_bf16(b[2], b[3]); return w; }
;     __device__ __forceinline__ void operator()(AccRef acc, const pg8::Unit& u, int wr, int wc, int fr, int fq) const {
;     ...
;             for (int m = 0; m < 4; ++m) { const size_t off = (size_t)(row0 + ai * 128 + m * 16) * 1024 + col0;
; #pragma unroll
;                 for (int bj = 0; bj < 2; ++bj) { const u32x4 gq = *(const u32x4*)(GCg + off + bj * 32); f32x4 v0 = acc[ai][bj][m][0], v1 = acc[ai][bj][m][1];
;                     v0[0] *= bf_lo(gq.x); v0[1] *= bf_hi(gq.x); v0[2] *= bf_lo(gq.y); v0[3] *= bf_hi(gq.y); v1[0] *= bf_lo(gq.z); v1[1] *= bf_hi(gq.z); v1[2] *= bf_lo(gq.w); v1[3] *= bf_hi(gq.w);
;                     *(u32x4*)(H + off + bj * 32) = pack8(v0, v1); } }
;     }
.LBB0_523:
	s_andn2_b64 vcc, exec, s[36:37]
	v_ashrrev_i32_e32 v173, 31, v172
	v_ashrrev_i32_e32 v171, 31, v170
	v_lshlrev_b64 v[128:129], 10, v[172:173]
	v_lshl_add_u64 v[128:129], v[128:129], 0, v[170:171]
	v_lshlrev_b64 v[128:129], 1, v[128:129]
	v_lshl_add_u64 v[134:135], s[4:5], 0, v[128:129]
	global_load_dwordx4 v[130:133], v[134:135], off
	s_nop 0
	global_load_dwordx4 v[134:137], v[134:135], off offset:64
	v_lshl_add_u64 v[138:139], s[58:59], 0, v[128:129]
	v_lshl_add_u64 v[140:141], v[128:129], 0, s[14:15]
	v_lshl_add_u64 v[142:143], s[4:5], 0, v[140:141]
	s_mov_b64 s[36:37], -1
	s_waitcnt vmcnt(0)
	v_lshlrev_b32_e32 v144, 16, v130
	v_and_b32_e32 v145, 0xffff0000, v130
	v_lshlrev_b32_e32 v130, 16, v131
	v_and_b32_e32 v131, 0xffff0000, v131
	v_lshlrev_b32_e32 v146, 16, v132
	v_and_b32_e32 v147, 0xffff0000, v132
	v_lshlrev_b32_e32 v132, 16, v133
	v_and_b32_e32 v133, 0xffff0000, v133
	v_lshlrev_b32_e32 v148, 16, v134
	v_and_b32_e32 v149, 0xffff0000, v134
	v_lshlrev_b32_e32 v134, 16, v135
	v_and_b32_e32 v135, 0xffff0000, v135
	v_lshlrev_b32_e32 v150, 16, v136
	v_and_b32_e32 v151, 0xffff0000, v136
	v_lshlrev_b32_e32 v136, 16, v137
	v_and_b32_e32 v137, 0xffff0000, v137
	v_pk_mul_f32 v[124:125], v[124:125], v[144:145]
	v_pk_mul_f32 v[126:127], v[126:127], v[130:131]
	v_pk_mul_f32 v[120:121], v[120:121], v[146:147]
	v_pk_mul_f32 v[122:123], v[122:123], v[132:133]
	v_pk_mul_f32 v[116:117], v[116:117], v[148:149]
	v_pk_mul_f32 v[118:119], v[118:119], v[134:135]
	v_pk_mul_f32 v[130:131], v[112:113], v[150:151]
	v_pk_mul_f32 v[132:133], v[114:115], v[136:137]
	v_cvt_pk_bf16_f32 v112, v124, v125
	v_cvt_pk_bf16_f32 v113, v126, v127
	v_cvt_pk_bf16_f32 v114, v120, v121
	v_cvt_pk_bf16_f32 v115, v122, v123
	v_cvt_pk_bf16_f32 v116, v116, v117
	v_cvt_pk_bf16_f32 v117, v118, v119
	v_cvt_pk_bf16_f32 v118, v130, v131
	v_cvt_pk_bf16_f32 v119, v132, v133
	global_store_dwordx4 v[138:139], v[112:115], off sc1
	global_store_dwordx4 v[138:139], v[116:119], off offset:64 sc1
	global_load_dwordx4 v[112:115], v[142:143], off
	s_nop 0
	global_load_dwordx4 v[116:119], v[142:143], off offset:64
	v_lshl_add_u64 v[120:121], v[128:129], 0, s[16:17]
	v_lshl_add_u64 v[122:123], s[58:59], 0, v[140:141]
	v_lshl_add_u64 v[124:125], s[4:5], 0, v[120:121]
	s_waitcnt vmcnt(1)
	v_lshlrev_b32_e32 v126, 16, v112
	v_and_b32_e32 v127, 0xffff0000, v112
	v_lshlrev_b32_e32 v112, 16, v113
	v_and_b32_e32 v113, 0xffff0000, v113
	v_lshlrev_b32_e32 v130, 16, v114
	v_and_b32_e32 v131, 0xffff0000, v114
	v_lshlrev_b32_e32 v114, 16, v115
	v_and_b32_e32 v115, 0xffff0000, v115
	s_waitcnt vmcnt(0)
	v_lshlrev_b32_e32 v132, 16, v116
	v_and_b32_e32 v133, 0xffff0000, v116
	v_lshlrev_b32_e32 v116, 16, v117
	v_and_b32_e32 v117, 0xffff0000, v117
	v_lshlrev_b32_e32 v134, 16, v118
	v_and_b32_e32 v135, 0xffff0000, v118
	v_lshlrev_b32_e32 v118, 16, v119
	v_and_b32_e32 v119, 0xffff0000, v119
	v_pk_mul_f32 v[108:109], v[108:109], v[126:127]
	v_pk_mul_f32 v[110:111], v[110:111], v[112:113]
	v_pk_mul_f32 v[104:105], v[104:105], v[130:131]
	v_pk_mul_f32 v[106:107], v[106:107], v[114:115]
	v_pk_mul_f32 v[100:101], v[100:101], v[132:133]
	v_pk_mul_f32 v[102:103], v[102:103], v[116:117]
	v_pk_mul_f32 v[112:113], v[96:97], v[134:135]
	v_pk_mul_f32 v[114:115], v[98:99], v[118:119]
	v_cvt_pk_bf16_f32 v96, v108, v109
	v_cvt_pk_bf16_f32 v97, v110, v111
	v_cvt_pk_bf16_f32 v98, v104, v105
	v_cvt_pk_bf16_f32 v99, v106, v107
	v_cvt_pk_bf16_f32 v100, v100, v101
	v_cvt_pk_bf16_f32 v101, v102, v103
	v_cvt_pk_bf16_f32 v102, v112, v113
	v_cvt_pk_bf16_f32 v103, v114, v115
	global_store_dwordx4 v[122:123], v[96:99], off sc1
	global_store_dwordx4 v[122:123], v[100:103], off offset:64 sc1
	global_load_dwordx4 v[96:99], v[124:125], off
	s_nop 0
	global_load_dwordx4 v[100:103], v[124:125], off offset:64
	v_lshl_add_u64 v[104:105], v[128:129], 0, s[18:19]
	v_lshl_add_u64 v[106:107], s[58:59], 0, v[120:121]
	v_lshl_add_u64 v[108:109], s[4:5], 0, v[104:105]
	s_waitcnt vmcnt(1)
	v_lshlrev_b32_e32 v110, 16, v96
	v_and_b32_e32 v111, 0xffff0000, v96
	v_lshlrev_b32_e32 v96, 16, v97
	v_and_b32_e32 v97, 0xffff0000, v97
	v_lshlrev_b32_e32 v112, 16, v98
	v_and_b32_e32 v113, 0xffff0000, v98
	v_lshlrev_b32_e32 v98, 16, v99
	v_and_b32_e32 v99, 0xffff0000, v99
	s_waitcnt vmcnt(0)
	v_lshlrev_b32_e32 v114, 16, v100
	v_and_b32_e32 v115, 0xffff0000, v100
	v_lshlrev_b32_e32 v100, 16, v101
	v_and_b32_e32 v101, 0xffff0000, v101
	v_lshlrev_b32_e32 v116, 16, v102
	v_and_b32_e32 v117, 0xffff0000, v102
	v_lshlrev_b32_e32 v102, 16, v103
	v_and_b32_e32 v103, 0xffff0000, v103
	v_pk_mul_f32 v[92:93], v[92:93], v[110:111]
	v_pk_mul_f32 v[94:95], v[94:95], v[96:97]
	v_pk_mul_f32 v[88:89], v[88:89], v[112:113]
	v_pk_mul_f32 v[90:91], v[90:91], v[98:99]
	v_pk_mul_f32 v[84:85], v[84:85], v[114:115]
	v_pk_mul_f32 v[86:87], v[86:87], v[100:101]
	v_pk_mul_f32 v[96:97], v[80:81], v[116:117]
	v_pk_mul_f32 v[98:99], v[82:83], v[102:103]
	v_cvt_pk_bf16_f32 v80, v92, v93
	v_cvt_pk_bf16_f32 v81, v94, v95
	v_cvt_pk_bf16_f32 v82, v88, v89
	v_cvt_pk_bf16_f32 v83, v90, v91
	v_cvt_pk_bf16_f32 v84, v84, v85
	v_cvt_pk_bf16_f32 v85, v86, v87
	v_cvt_pk_bf16_f32 v86, v96, v97
	v_cvt_pk_bf16_f32 v87, v98, v99
	global_store_dwordx4 v[106:107], v[80:83], off sc1
	global_store_dwordx4 v[106:107], v[84:87], off offset:64 sc1
	global_load_dwordx4 v[80:83], v[108:109], off
	s_nop 0
	global_load_dwordx4 v[84:87], v[108:109], off offset:64
	v_lshl_add_u64 v[88:89], v[128:129], 0, s[6:7]
	v_lshl_add_u64 v[90:91], s[58:59], 0, v[104:105]
	v_lshl_add_u64 v[92:93], s[4:5], 0, v[88:89]
	s_waitcnt vmcnt(1)
; __device__ __forceinline__ float bf_lo(unsigned u) { return __uint_as_float(u << 16); }
; __device__ __forceinline__ float bf_hi(unsigned u) { return __uint_as_float(u & 0xffff0000u); }
; __device__ __forceinline__ u32x4 pack8(f32x4 a, f32x4 b) { u32x4 w; w.x = cvt_pk_bf16(a[0], a[1]); w.y = cvt_pk_bf16(a[2], a[3]); w.z = cvt_pk_bf16(b[0], b[1]); w.w = cvt_pk_bf16(b[2], b[3]); return w; }
;     __device__ __forceinline__ void operator()(AccRef acc, const pg8::Unit& u, int wr, int wc, int fr, int fq) const {
;     ...
;             for (int m = 0; m < 4; ++m) { const size_t off = (size_t)(row0 + ai * 128 + m * 16) * 1024 + col0;
; #pragma unroll
;                 for (int bj = 0; bj < 2; ++bj) { const u32x4 gq = *(const u32x4*)(GCg + off + bj * 32); f32x4 v0 = acc[ai][bj][m][0], v1 = acc[ai][bj][m][1];
;                     v0[0] *= bf_lo(gq.x); v0[1] *= bf_hi(gq.x); v0[2] *= bf_lo(gq.y); v0[3] *= bf_hi(gq.y); v1[0] *= bf_lo(gq.z); v1[1] *= bf_hi(gq.z); v1[2] *= bf_lo(gq.w); v1[3] *= bf_hi(gq.w);
;                     *(u32x4*)(H + off + bj * 32) = pack8(v0, v1); } }
;     }
	v_lshlrev_b32_e32 v94, 16, v80
	v_and_b32_e32 v95, 0xffff0000, v80
	v_lshlrev_b32_e32 v80, 16, v81
	v_and_b32_e32 v81, 0xffff0000, v81
	v_lshlrev_b32_e32 v96, 16, v82
	v_and_b32_e32 v97, 0xffff0000, v82
	v_lshlrev_b32_e32 v82, 16, v83
	v_and_b32_e32 v83, 0xffff0000, v83
	s_waitcnt vmcnt(0)
	v_lshlrev_b32_e32 v98, 16, v84
	v_and_b32_e32 v99, 0xffff0000, v84
	v_lshlrev_b32_e32 v84, 16, v85
	v_and_b32_e32 v85, 0xffff0000, v85
	v_lshlrev_b32_e32 v100, 16, v86
	v_and_b32_e32 v101, 0xffff0000, v86
	v_lshlrev_b32_e32 v86, 16, v87
	v_and_b32_e32 v87, 0xffff0000, v87
	v_pk_mul_f32 v[76:77], v[76:77], v[94:95]
	v_pk_mul_f32 v[78:79], v[78:79], v[80:81]
	v_pk_mul_f32 v[72:73], v[72:73], v[96:97]
	v_pk_mul_f32 v[74:75], v[74:75], v[82:83]
	v_pk_mul_f32 v[68:69], v[68:69], v[98:99]
	v_pk_mul_f32 v[70:71], v[70:71], v[84:85]
	v_pk_mul_f32 v[80:81], v[64:65], v[100:101]
	v_pk_mul_f32 v[82:83], v[66:67], v[86:87]
	v_cvt_pk_bf16_f32 v64, v76, v77
	v_cvt_pk_bf16_f32 v65, v78, v79
	v_cvt_pk_bf16_f32 v66, v72, v73
	v_cvt_pk_bf16_f32 v67, v74, v75
	v_cvt_pk_bf16_f32 v68, v68, v69
	v_cvt_pk_bf16_f32 v69, v70, v71
	v_cvt_pk_bf16_f32 v70, v80, v81
	v_cvt_pk_bf16_f32 v71, v82, v83
	global_store_dwordx4 v[90:91], v[64:67], off sc1
	global_store_dwordx4 v[90:91], v[68:71], off offset:64 sc1
	global_load_dwordx4 v[64:67], v[92:93], off
	s_nop 0
	global_load_dwordx4 v[68:71], v[92:93], off offset:64
	v_lshl_add_u64 v[72:73], v[128:129], 0, s[20:21]
	v_lshl_add_u64 v[74:75], s[58:59], 0, v[88:89]
	v_lshl_add_u64 v[76:77], s[4:5], 0, v[72:73]
	s_waitcnt vmcnt(1)
	v_lshlrev_b32_e32 v78, 16, v64
	v_and_b32_e32 v79, 0xffff0000, v64
	v_lshlrev_b32_e32 v64, 16, v65
	v_and_b32_e32 v65, 0xffff0000, v65
	v_lshlrev_b32_e32 v80, 16, v66
	v_and_b32_e32 v81, 0xffff0000, v66
	v_lshlrev_b32_e32 v66, 16, v67
	v_and_b32_e32 v67, 0xffff0000, v67
	s_waitcnt vmcnt(0)
	v_lshlrev_b32_e32 v82, 16, v68
	v_and_b32_e32 v83, 0xffff0000, v68
	v_lshlrev_b32_e32 v68, 16, v69
	v_and_b32_e32 v69, 0xffff0000, v69
	v_lshlrev_b32_e32 v84, 16, v70
	v_and_b32_e32 v85, 0xffff0000, v70
	v_lshlrev_b32_e32 v70, 16, v71
	v_and_b32_e32 v71, 0xffff0000, v71
	v_pk_mul_f32 v[60:61], v[60:61], v[78:79]
	v_pk_mul_f32 v[62:63], v[62:63], v[64:65]
	v_pk_mul_f32 v[56:57], v[56:57], v[80:81]
	v_pk_mul_f32 v[58:59], v[58:59], v[66:67]
	v_pk_mul_f32 v[52:53], v[52:53], v[82:83]
	v_pk_mul_f32 v[54:55], v[54:55], v[68:69]
	v_pk_mul_f32 v[64:65], v[48:49], v[84:85]
	v_pk_mul_f32 v[66:67], v[50:51], v[70:71]
	v_cvt_pk_bf16_f32 v48, v60, v61
	v_cvt_pk_bf16_f32 v49, v62, v63
	v_cvt_pk_bf16_f32 v50, v56, v57
	v_cvt_pk_bf16_f32 v51, v58, v59
	v_cvt_pk_bf16_f32 v52, v52, v53
	v_cvt_pk_bf16_f32 v53, v54, v55
	v_cvt_pk_bf16_f32 v54, v64, v65
	v_cvt_pk_bf16_f32 v55, v66, v67
	global_store_dwordx4 v[74:75], v[48:51], off sc1
	global_store_dwordx4 v[74:75], v[52:55], off offset:64 sc1
	global_load_dwordx4 v[48:51], v[76:77], off
	s_nop 0
	global_load_dwordx4 v[52:55], v[76:77], off offset:64
	v_lshl_add_u64 v[56:57], v[128:129], 0, s[22:23]
	v_lshl_add_u64 v[58:59], s[58:59], 0, v[72:73]
	v_lshl_add_u64 v[60:61], s[4:5], 0, v[56:57]
	s_waitcnt vmcnt(1)
	v_lshlrev_b32_e32 v62, 16, v48
	v_and_b32_e32 v63, 0xffff0000, v48
	v_lshlrev_b32_e32 v48, 16, v49
	v_and_b32_e32 v49, 0xffff0000, v49
	v_lshlrev_b32_e32 v64, 16, v50
	v_and_b32_e32 v65, 0xffff0000, v50
	v_lshlrev_b32_e32 v50, 16, v51
	v_and_b32_e32 v51, 0xffff0000, v51
	s_waitcnt vmcnt(0)
; __device__ __forceinline__ float bf_lo(unsigned u) { return __uint_as_float(u << 16); }
; __device__ __forceinline__ float bf_hi(unsigned u) { return __uint_as_float(u & 0xffff0000u); }
; __device__ __forceinline__ u32x4 pack8(f32x4 a, f32x4 b) { u32x4 w; w.x = cvt_pk_bf16(a[0], a[1]); w.y = cvt_pk_bf16(a[2], a[3]); w.z = cvt_pk_bf16(b[0], b[1]); w.w = cvt_pk_bf16(b[2], b[3]); return w; }
;     __device__ __forceinline__ void operator()(AccRef acc, const pg8::Unit& u, int wr, int wc, int fr, int fq) const {
;     ...
;             for (int m = 0; m < 4; ++m) { const size_t off = (size_t)(row0 + ai * 128 + m * 16) * 1024 + col0;
; #pragma unroll
;                 for (int bj = 0; bj < 2; ++bj) { const u32x4 gq = *(const u32x4*)(GCg + off + bj * 32); f32x4 v0 = acc[ai][bj][m][0], v1 = acc[ai][bj][m][1];
;                     v0[0] *= bf_lo(gq.x); v0[1] *= bf_hi(gq.x); v0[2] *= bf_lo(gq.y); v0[3] *= bf_hi(gq.y); v1[0] *= bf_lo(gq.z); v1[1] *= bf_hi(gq.z); v1[2] *= bf_lo(gq.w); v1[3] *= bf_hi(gq.w);
;                     *(u32x4*)(H + off + bj * 32) = pack8(v0, v1); } }
;     }
	v_lshlrev_b32_e32 v66, 16, v52
	v_and_b32_e32 v67, 0xffff0000, v52
	v_lshlrev_b32_e32 v52, 16, v53
	v_and_b32_e32 v53, 0xffff0000, v53
	v_lshlrev_b32_e32 v68, 16, v54
	v_and_b32_e32 v69, 0xffff0000, v54
	v_lshlrev_b32_e32 v54, 16, v55
	v_and_b32_e32 v55, 0xffff0000, v55
	v_pk_mul_f32 v[44:45], v[44:45], v[62:63]
	v_pk_mul_f32 v[46:47], v[46:47], v[48:49]
	v_pk_mul_f32 v[40:41], v[40:41], v[64:65]
	v_pk_mul_f32 v[42:43], v[42:43], v[50:51]
	v_pk_mul_f32 v[36:37], v[36:37], v[66:67]
	v_pk_mul_f32 v[38:39], v[38:39], v[52:53]
	v_pk_mul_f32 v[48:49], v[32:33], v[68:69]
	v_pk_mul_f32 v[50:51], v[34:35], v[54:55]
	v_cvt_pk_bf16_f32 v32, v44, v45
	v_cvt_pk_bf16_f32 v33, v46, v47
	v_cvt_pk_bf16_f32 v34, v40, v41
	v_cvt_pk_bf16_f32 v35, v42, v43
	v_cvt_pk_bf16_f32 v36, v36, v37
	v_cvt_pk_bf16_f32 v37, v38, v39
	v_cvt_pk_bf16_f32 v38, v48, v49
	v_cvt_pk_bf16_f32 v39, v50, v51
	global_store_dwordx4 v[58:59], v[32:35], off sc1
	global_store_dwordx4 v[58:59], v[36:39], off offset:64 sc1
	global_load_dwordx4 v[32:35], v[60:61], off
	s_nop 0
	global_load_dwordx4 v[36:39], v[60:61], off offset:64
	v_lshl_add_u64 v[40:41], v[128:129], 0, s[24:25]
	v_lshl_add_u64 v[42:43], s[58:59], 0, v[56:57]
	v_lshl_add_u64 v[44:45], s[4:5], 0, v[40:41]
	s_waitcnt vmcnt(1)
	v_lshlrev_b32_e32 v46, 16, v32
	v_and_b32_e32 v47, 0xffff0000, v32
	v_lshlrev_b32_e32 v32, 16, v33
	v_and_b32_e32 v33, 0xffff0000, v33
	v_lshlrev_b32_e32 v48, 16, v34
	v_and_b32_e32 v49, 0xffff0000, v34
	v_lshlrev_b32_e32 v34, 16, v35
	v_and_b32_e32 v35, 0xffff0000, v35
	s_waitcnt vmcnt(0)
	v_lshlrev_b32_e32 v50, 16, v36
	v_and_b32_e32 v51, 0xffff0000, v36
	v_lshlrev_b32_e32 v36, 16, v37
	v_and_b32_e32 v37, 0xffff0000, v37
	v_lshlrev_b32_e32 v52, 16, v38
	v_and_b32_e32 v53, 0xffff0000, v38
	v_lshlrev_b32_e32 v38, 16, v39
	v_and_b32_e32 v39, 0xffff0000, v39
	v_pk_mul_f32 v[28:29], v[28:29], v[46:47]
	v_pk_mul_f32 v[30:31], v[30:31], v[32:33]
	v_pk_mul_f32 v[24:25], v[24:25], v[48:49]
	v_pk_mul_f32 v[26:27], v[26:27], v[34:35]
	v_pk_mul_f32 v[20:21], v[20:21], v[50:51]
	v_pk_mul_f32 v[22:23], v[22:23], v[36:37]
	v_pk_mul_f32 v[32:33], v[16:17], v[52:53]
	v_pk_mul_f32 v[34:35], v[18:19], v[38:39]
	v_cvt_pk_bf16_f32 v16, v28, v29
	v_cvt_pk_bf16_f32 v17, v30, v31
	v_cvt_pk_bf16_f32 v18, v24, v25
	v_cvt_pk_bf16_f32 v19, v26, v27
	v_cvt_pk_bf16_f32 v20, v20, v21
	v_cvt_pk_bf16_f32 v21, v22, v23
	v_cvt_pk_bf16_f32 v22, v32, v33
	v_cvt_pk_bf16_f32 v23, v34, v35
	global_store_dwordx4 v[42:43], v[16:19], off sc1
	global_store_dwordx4 v[42:43], v[20:23], off offset:64 sc1
	global_load_dwordx4 v[16:19], v[44:45], off
	s_nop 0
	global_load_dwordx4 v[20:23], v[44:45], off offset:64
	v_lshl_add_u64 v[24:25], s[58:59], 0, v[40:41]
	s_waitcnt vmcnt(1)
	v_lshlrev_b32_e32 v26, 16, v16
	v_and_b32_e32 v27, 0xffff0000, v16
	v_lshlrev_b32_e32 v16, 16, v17
	v_and_b32_e32 v17, 0xffff0000, v17
	v_lshlrev_b32_e32 v28, 16, v18
	v_and_b32_e32 v29, 0xffff0000, v18
	v_lshlrev_b32_e32 v18, 16, v19
	v_and_b32_e32 v19, 0xffff0000, v19
	s_waitcnt vmcnt(0)
	v_lshlrev_b32_e32 v30, 16, v20
	v_and_b32_e32 v31, 0xffff0000, v20
	v_lshlrev_b32_e32 v20, 16, v21
	v_and_b32_e32 v21, 0xffff0000, v21
	v_lshlrev_b32_e32 v32, 16, v22
	v_and_b32_e32 v33, 0xffff0000, v22
	v_lshlrev_b32_e32 v22, 16, v23
	v_and_b32_e32 v23, 0xffff0000, v23
	v_pk_mul_f32 v[12:13], v[12:13], v[26:27]
	v_pk_mul_f32 v[14:15], v[14:15], v[16:17]
	v_pk_mul_f32 v[8:9], v[8:9], v[28:29]
	v_pk_mul_f32 v[10:11], v[10:11], v[18:19]
	v_pk_mul_f32 v[4:5], v[4:5], v[30:31]
	v_pk_mul_f32 v[6:7], v[6:7], v[20:21]
	v_pk_mul_f32 v[16:17], v[0:1], v[32:33]
	v_pk_mul_f32 v[18:19], v[2:3], v[22:23]
	v_cvt_pk_bf16_f32 v0, v12, v13
	v_cvt_pk_bf16_f32 v1, v14, v15
	v_cvt_pk_bf16_f32 v2, v8, v9
	v_cvt_pk_bf16_f32 v3, v10, v11
	v_cvt_pk_bf16_f32 v4, v4, v5
	v_cvt_pk_bf16_f32 v5, v6, v7
	v_cvt_pk_bf16_f32 v6, v16, v17
	v_cvt_pk_bf16_f32 v7, v18, v19
	global_store_dwordx4 v[24:25], v[0:3], off sc1
	global_store_dwordx4 v[24:25], v[4:7], off offset:64 sc1
	s_cbranch_vccnz .LBB0_507
	s_andn2_b64 vcc, exec, s[8:9]
	s_cbranch_vccnz .LBB0_506
	s_barrier
	s_branch .LBB0_506
